# combined: post_proj cross-row prefetch + pipelined branch-GEMM epilogue (gate and Y loads issued ahead)
# speedup vs baseline: 1.0114x; 1.0114x over previous
.LBB0_341:
	v_lshrrev_b32_e32 v0, 6, v168
	v_lshl_add_u32 v0, s12, 3, v0
	s_mov_b32 s0, 0x8800
	v_cmp_gt_i32_e32 vcc, s0, v0
	s_and_saveexec_b64 s[0:1], vcc
	s_cbranch_execz .LBB0_362
	v_mbcnt_lo_u32_b32 v2, -1, 0
	v_mbcnt_hi_u32_b32 v2, -1, v2
	v_and_b32_e32 v4, 64, v2
	v_add_u32_e32 v4, 64, v4
	v_xor_b32_e32 v5, 1, v2
	v_cmp_lt_i32_e32 vcc, v5, v4
	v_and_b32_e32 v20, 7, v168
	v_and_b32_e32 v1, 63, v168
	v_cndmask_b32_e32 v5, v2, v5, vcc
	v_lshlrev_b32_e32 v38, 2, v5
	v_xor_b32_e32 v5, 2, v2
	v_cmp_lt_i32_e32 vcc, v5, v4
	v_lshlrev_b32_e32 v14, 2, v1
	v_and_b32_e32 v26, 12, v14
	v_cndmask_b32_e32 v5, v2, v5, vcc
	v_lshlrev_b32_e32 v39, 2, v5
	v_xor_b32_e32 v5, 4, v2
	v_cmp_lt_i32_e32 vcc, v5, v4
	v_readlane_b32 s16, v244, 1
	v_mov_b32_e32 v3, 0
	v_cndmask_b32_e32 v5, v2, v5, vcc
	v_lshlrev_b32_e32 v40, 2, v5
	v_xor_b32_e32 v5, 8, v2
	v_cmp_lt_i32_e32 vcc, v5, v4
	v_readlane_b32 s18, v244, 3
	v_readlane_b32 s19, v244, 4
	v_cndmask_b32_e32 v5, v2, v5, vcc
	v_lshlrev_b32_e32 v41, 2, v5
	v_xor_b32_e32 v5, 16, v2
	v_cmp_lt_i32_e32 vcc, v5, v4
	v_readlane_b32 s22, v244, 7
	v_readlane_b32 s23, v244, 8
	v_cndmask_b32_e32 v5, v2, v5, vcc
	v_lshlrev_b32_e32 v42, 2, v5
	v_xor_b32_e32 v5, 32, v2
	v_cmp_lt_i32_e32 vcc, v5, v4
	v_lshlrev_b32_e32 v4, 3, v168
	v_and_b32_e32 v22, 0x1c0, v4
	v_cndmask_b32_e32 v2, v2, v5, vcc
	v_lshlrev_b32_e32 v43, 2, v2
	v_lshlrev_b32_e32 v2, 1, v168
	v_and_b32_e32 v18, 16, v2
	v_cvt_f32_ubyte0_e32 v2, v20
	v_mul_f32_e32 v2, 0xbfd49a78, v2
	v_exp_f32_e32 v44, v2
	v_bfe_u32 v2, v168, 2, 1
	v_lshlrev_b32_e32 v24, 5, v2
	v_cmp_eq_u32_e64 s[4:5], 0, v2
	v_cvt_f32_ubyte0_e32 v2, v26
	v_mul_f32_e32 v2, 0xbf549a78, v2
	v_exp_f32_e32 v45, v2
	v_or_b32_e32 v2, 1, v26
	v_cvt_f32_ubyte0_e32 v2, v2
	v_mul_f32_e32 v2, 0xbf549a78, v2
	v_exp_f32_e32 v46, v2
	v_or_b32_e32 v2, 2, v26
	v_cvt_f32_ubyte0_e32 v2, v2
	v_mul_f32_e32 v2, 0xbf549a78, v2
	v_exp_f32_e32 v47, v2
	v_or_b32_e32 v2, 3, v26
	v_cvt_f32_ubyte0_e32 v2, v2
	v_mul_f32_e32 v2, 0xbf549a78, v2
	v_exp_f32_e32 v48, v2
	v_lshlrev_b32_e32 v2, 4, v1
	v_or_b32_e32 v8, v24, v26
	v_lshl_add_u64 v[4:5], s[18:19], 0, v[2:3]
	v_lshlrev_b32_e32 v2, 3, v1
	v_lshlrev_b32_e32 v16, 1, v1
	v_readlane_b32 s17, v244, 2
	v_readlane_b32 s26, v244, 11
	v_readlane_b32 s27, v244, 12
	v_readlane_b32 s28, v244, 13
	v_readlane_b32 s29, v244, 14
	v_lshl_add_u64 v[6:7], s[22:23], 0, v[2:3]
	v_lshlrev_b32_e32 v2, 2, v8
	s_lshl_b32 s13, s70, 3
	v_cmp_gt_u32_e32 vcc, 16, v1
	v_cmp_gt_u32_e64 s[2:3], 8, v1
	v_lshl_add_u64 v[8:9], s[26:27], 0, v[2:3]
	v_lshl_add_u64 v[10:11], s[28:29], 0, v[2:3]
	s_mov_b64 s[14:15], 0
	v_mov_b64_e32 v[12:13], s[60:61]
	v_lshlrev_b32_e32 v14, 1, v14
	v_mov_b32_e32 v15, v3
	s_mov_b32 s16, 0xffff0000
	v_mov_b32_e32 v49, 0x358637bd
	s_mov_b32 s17, 0x800000
	s_movk_i32 s18, 0x7fff
	v_lshlrev_b32_e32 v16, 1, v16
	v_lshlrev_b32_e32 v18, 1, v18
	v_lshlrev_b32_e32 v20, 1, v20
	v_lshlrev_b32_e32 v2, 1, v22
	v_lshlrev_b32_e32 v22, 1, v24
	v_lshlrev_b32_e32 v24, 1, v26
	s_mov_b32 s34, 0x3e38aa3b
	v_mov_b32_e32 v50, 1
	v_mov_b32_e32 v17, v3
	v_readlane_b32 s20, v244, 5
	v_readlane_b32 s21, v244, 6
	v_readlane_b32 s24, v244, 9
	v_readlane_b32 s25, v244, 10
	v_readlane_b32 s30, v244, 15
	v_readlane_b32 s31, v244, 16
	global_load_dwordx4 v[70:73], v[4:5], off
	global_load_dwordx2 v[74:75], v[6:7], off
	global_load_dwordx4 v[76:79], v[8:9], off
	global_load_dwordx4 v[102:105], v[8:9], off offset:64
	global_load_dwordx4 v[106:109], v[10:11], off
	global_load_dwordx4 v[110:113], v[10:11], off offset:64
	v_add_u32_e32 v80, v18, v20
	v_mov_b32_e32 v81, 0
	v_add3_u32 v82, v2, v22, v24
	v_mov_b32_e32 v83, 0
	v_mov_b32_e32 v163, 0
	v_ashrrev_i32_e32 v1, 31, v0
	v_lshlrev_b64 v[164:165], 12, v[0:1]
	v_lshl_add_u64 v[164:165], s[58:59], 0, v[164:165]
	v_lshl_add_u64 v[28:29], v[164:165], 0, v[14:15]
	v_lshl_add_u64 v[54:55], v[164:165], 0, v[16:17]
	v_lshl_add_u64 v[84:85], v[164:165], 0, v[82:83]
	v_lshl_add_u64 v[114:115], v[164:165], 0, v[80:81]
	global_load_dwordx2 v[120:121], v[28:29], off
	global_load_dword v118, v[54:55], off offset:512
	global_load_dwordx2 v[86:87], v[84:85], off offset:832
	global_load_dwordx2 v[88:89], v[84:85], off offset:864
	global_load_dwordx2 v[90:91], v[84:85], off offset:2368
	global_load_dwordx2 v[92:93], v[84:85], off offset:2400
	s_and_saveexec_b64 s[8:9], vcc
	global_load_dwordx2 v[94:95], v[84:85], off offset:1856
	global_load_dwordx2 v[96:97], v[84:85], off offset:1888
	global_load_dwordx2 v[98:99], v[84:85], off offset:3392
	global_load_dwordx2 v[100:101], v[84:85], off offset:3424
	global_load_ushort v116, v[114:115], off offset:768
	global_load_ushort v117, v[114:115], off offset:784
	s_or_b64 exec, exec, s[8:9]
	s_branch .LBB0_344

.LBB0_344:
	s_waitcnt vmcnt(0)
	v_mov_b64_e32 v[32:33], v[120:121]
	v_mov_b64_e32 v[142:143], v[86:87]
	v_mov_b64_e32 v[144:145], v[88:89]
	v_mov_b64_e32 v[146:147], v[90:91]
	v_mov_b64_e32 v[148:149], v[92:93]
	v_mov_b64_e32 v[150:151], v[94:95]
	v_mov_b64_e32 v[152:153], v[96:97]
	v_mov_b64_e32 v[154:155], v[98:99]
	v_mov_b64_e32 v[156:157], v[100:101]
	v_mov_b32_e32 v158, v116
	v_mov_b32_e32 v159, v117
	v_mov_b32_e32 v160, v118
	v_ashrrev_i32_e32 v1, 31, v0
	v_lshlrev_b64 v[26:27], 12, v[0:1]
	v_lshl_add_u64 v[26:27], s[58:59], 0, v[26:27]
	v_add_u32_e32 v162, s13, v0
	v_min_i32_e32 v162, 0x87ff, v162
	v_lshlrev_b64 v[164:165], 12, v[162:163]
	v_lshl_add_u64 v[164:165], s[58:59], 0, v[164:165]
	v_lshl_add_u64 v[28:29], v[164:165], 0, v[14:15]
	v_lshl_add_u64 v[54:55], v[164:165], 0, v[16:17]
	v_lshl_add_u64 v[84:85], v[164:165], 0, v[82:83]
	v_lshl_add_u64 v[114:115], v[164:165], 0, v[80:81]
	global_load_dwordx2 v[120:121], v[28:29], off
	global_load_dword v118, v[54:55], off offset:512
	global_load_dwordx2 v[86:87], v[84:85], off offset:832
	global_load_dwordx2 v[88:89], v[84:85], off offset:864
	global_load_dwordx2 v[90:91], v[84:85], off offset:2368
	global_load_dwordx2 v[92:93], v[84:85], off offset:2400
	s_and_saveexec_b64 s[8:9], vcc
	global_load_dwordx2 v[94:95], v[84:85], off offset:1856
	global_load_dwordx2 v[96:97], v[84:85], off offset:1888
	global_load_dwordx2 v[98:99], v[84:85], off offset:3392
	global_load_dwordx2 v[100:101], v[84:85], off offset:3424
	global_load_ushort v116, v[114:115], off offset:768
	global_load_ushort v117, v[114:115], off offset:784
	s_or_b64 exec, exec, s[8:9]
	s_movk_i32 s6, 0x300
	v_mov_b64_e32 v[28:29], v[70:71]
	v_mov_b64_e32 v[30:31], v[72:73]
	v_lshlrev_b32_e32 v34, 16, v32
	v_and_b32_e32 v32, 0xffff0000, v32
	v_lshlrev_b32_e32 v35, 16, v33
	v_and_b32_e32 v33, 0xffff0000, v33
	v_mov_b32_e32 v36, v34
	v_mov_b32_e32 v37, v32
	v_mov_b32_e32 v52, v33
	v_mov_b32_e32 v53, v35
	v_pk_mul_f32 v[36:37], v[36:37], v[36:37]
	v_pk_mul_f32 v[52:53], v[52:53], v[52:53]
	v_add_f32_e32 v1, v36, v37
	v_add_f32_e32 v1, v53, v1
	v_add_f32_e32 v1, v52, v1
	ds_bpermute_b32 v19, v38, v1
	v_mad_i64_i32 v[36:37], s[6:7], v0, s6, v[12:13]
	v_mov_b32_e32 v56, v28
	v_mov_b32_e32 v57, v30
	s_waitcnt lgkmcnt(0)
	v_add_f32_e32 v1, v1, v19
	ds_bpermute_b32 v19, v39, v1
	v_mov_b32_e32 v30, v29
	v_lshl_add_u64 v[52:53], v[36:37], 0, v[14:15]
	s_waitcnt lgkmcnt(0)
	v_add_f32_e32 v1, v1, v19
	ds_bpermute_b32 v19, v40, v1
	s_waitcnt lgkmcnt(0)
	v_add_f32_e32 v1, v1, v19
	ds_bpermute_b32 v19, v41, v1
	s_waitcnt lgkmcnt(0)
	v_add_f32_e32 v1, v1, v19
	ds_bpermute_b32 v19, v42, v1
	s_waitcnt lgkmcnt(0)
	v_add_f32_e32 v1, v1, v19
	ds_bpermute_b32 v19, v43, v1
	s_waitcnt lgkmcnt(0)
	v_add_f32_e32 v1, v1, v19
	v_fmamk_f32 v1, v1, 0x3b800000, v49
	v_mul_f32_e32 v19, 0x4b800000, v1
	v_cmp_gt_f32_e64 s[6:7], s17, v1
	s_nop 1
	v_cndmask_b32_e64 v1, v1, v19, s[6:7]
	v_rsq_f32_e32 v1, v1
	s_nop 0
	v_mul_f32_e32 v19, 0x45800000, v1
	v_cndmask_b32_e64 v28, v1, v19, s[6:7]
	v_pk_mul_f32 v[34:35], v[28:29], v[34:35] op_sel_hi:[0,1]
	v_pk_mul_f32 v[28:29], v[28:29], v[32:33] op_sel_hi:[0,1]
	v_pk_mul_f32 v[28:29], v[30:31], v[28:29]
	v_pk_mul_f32 v[32:33], v[56:57], v[34:35]
	v_and_b32_sdwa v21, v29, v50 dst_sel:DWORD dst_unused:UNUSED_PAD src0_sel:WORD_1 src1_sel:DWORD
	v_and_b32_sdwa v23, v28, v50 dst_sel:DWORD dst_unused:UNUSED_PAD src0_sel:WORD_1 src1_sel:DWORD
	v_and_b32_sdwa v1, v33, v50 dst_sel:DWORD dst_unused:UNUSED_PAD src0_sel:WORD_1 src1_sel:DWORD
	v_and_b32_sdwa v19, v32, v50 dst_sel:DWORD dst_unused:UNUSED_PAD src0_sel:WORD_1 src1_sel:DWORD
	v_add3_u32 v21, v29, v21, s18
	v_add3_u32 v23, v28, v23, s18
	v_add3_u32 v19, v32, v19, s18
	v_add3_u32 v1, v33, v1, s18
	v_and_b32_e32 v21, 0xffff0000, v21
	v_and_b32_e32 v23, 0xffff0000, v23
	v_or_b32_sdwa v29, v21, v1 dst_sel:DWORD dst_unused:UNUSED_PAD src0_sel:DWORD src1_sel:WORD_1
	v_or_b32_sdwa v28, v23, v19 dst_sel:DWORD dst_unused:UNUSED_PAD src0_sel:DWORD src1_sel:WORD_1
	global_store_dwordx2 v[52:53], v[28:29], off
	v_mov_b32_e32 v1, v160
	s_nop 0
	v_mov_b64_e32 v[28:29], v[74:75]
	s_mov_b32 s6, 0x78787879
	v_mul_hi_i32 v21, v0, s6
	v_lshrrev_b32_e32 v23, 31, v21
	v_ashrrev_i32_e32 v21, 11, v21
	v_add_u32_e32 v21, v21, v23
	v_mul_i32_i24_e32 v21, 0x1100, v21
	s_movk_i32 s7, 0xff
	v_sub_u32_e32 v21, v0, v21
	v_cmp_lt_i32_e64 s[6:7], s7, v21
	v_add_u32_e32 v23, 0xffffff00, v21
	v_and_b32_e32 v21, 63, v21
	v_ashrrev_i32_e32 v23, 6, v23
	v_cvt_f32_i32_e32 v34, v23
	s_and_b64 s[20:21], s[6:7], vcc
	s_nop 0
	v_lshlrev_b32_e32 v30, 16, v1
	v_and_b32_e32 v31, 0xffff0000, v1
	v_pk_mul_f32 v[32:33], v[30:31], v[30:31]
	s_nop 0
	v_add_f32_e32 v1, v32, v33
	ds_bpermute_b32 v19, v38, v1
	v_lshl_add_u64 v[32:33], v[36:37], 0, v[16:17]
	s_waitcnt lgkmcnt(0)
	v_add_f32_e32 v1, v1, v19
	ds_bpermute_b32 v19, v39, v1
	s_waitcnt lgkmcnt(0)
	v_add_f32_e32 v1, v1, v19
	ds_bpermute_b32 v19, v40, v1
	s_waitcnt lgkmcnt(0)
	v_add_f32_e32 v1, v1, v19
	ds_bpermute_b32 v19, v41, v1
	s_waitcnt lgkmcnt(0)
	v_add_f32_e32 v1, v1, v19
	ds_bpermute_b32 v19, v42, v1
	s_waitcnt lgkmcnt(0)
	v_add_f32_e32 v1, v1, v19
	ds_bpermute_b32 v19, v43, v1
	s_waitcnt lgkmcnt(0)
	v_add_f32_e32 v1, v1, v19
	v_fmamk_f32 v1, v1, 0x3c000000, v49
	v_mul_f32_e32 v19, 0x4b800000, v1
	v_cmp_gt_f32_e64 s[8:9], s17, v1
	s_nop 1
	v_cndmask_b32_e64 v1, v1, v19, s[8:9]
	v_rsq_f32_e32 v19, v1
	v_cvt_f32_ubyte0_e32 v1, v21
	v_mul_f32_e32 v21, 0x45800000, v19
	v_cndmask_b32_e64 v36, v19, v21, s[8:9]
	v_pk_mul_f32 v[30:31], v[36:37], v[30:31] op_sel_hi:[0,1]
	s_nop 0
	v_pk_mul_f32 v[28:29], v[28:29], v[30:31]
	s_nop 0
	v_and_b32_sdwa v21, v28, v50 dst_sel:DWORD dst_unused:UNUSED_PAD src0_sel:WORD_1 src1_sel:DWORD
	v_and_b32_sdwa v19, v29, v50 dst_sel:DWORD dst_unused:UNUSED_PAD src0_sel:WORD_1 src1_sel:DWORD
	v_add3_u32 v21, v28, v21, s18
	v_add3_u32 v19, v29, v19, s18
	v_lshrrev_b32_e32 v21, 16, v21
	v_and_or_b32 v19, v19, s16, v21
	global_store_dword v[32:33], v19, off offset:512
	s_and_saveexec_b64 s[8:9], s[20:21]
	s_cbranch_execz .LBB0_346
	v_mov_b32_e32 v19, v3
	v_lshl_add_u64 v[28:29], v[26:27], 0, v[18:19]
	v_mov_b32_e32 v21, v3
	v_lshl_add_u64 v[28:29], v[28:29], 0, v[20:21]
	v_mov_b32_e32 v19, v158
	v_mov_b32_e32 v21, v159
	v_cndmask_b32_e64 v23, v1, v34, s[2:3]
	v_mul_f32_e32 v23, v44, v23
	v_mul_f32_e32 v23, 0.15915494, v23
	v_sin_f32_e32 v25, v23
	v_cos_f32_e32 v23, v23
	s_nop 0
	v_lshlrev_b32_e32 v19, 16, v19
	s_nop 0
	v_lshlrev_b32_e32 v21, 16, v21
	v_mul_f32_e32 v30, v25, v21
	v_mul_f32_e32 v21, v23, v21
	v_fma_f32 v23, v23, v19, -v30
	v_fmac_f32_e32 v21, v25, v19
	v_bfe_u32 v19, v23, 16, 1
	v_bfe_u32 v25, v21, 16, 1
	v_add3_u32 v19, v23, v19, s18
	v_add3_u32 v21, v21, v25, s18
	global_store_short_d16_hi v[28:29], v19, off offset:768
	global_store_short_d16_hi v[28:29], v21, off offset:784
.LBB0_346:
	s_or_b64 exec, exec, s[8:9]
	v_lshl_add_u64 v[26:27], v[26:27], 0, v[2:3]
	v_mov_b32_e32 v23, v3
	v_lshl_add_u64 v[26:27], v[26:27], 0, v[22:23]
	v_mov_b32_e32 v25, v3
	v_lshl_add_u64 v[26:27], v[26:27], 0, v[24:25]
	v_mov_b64_e32 v[28:29], v[142:143]
	v_mov_b64_e32 v[36:37], v[144:145]
	v_mov_b64_e32 v[30:31], v[76:77]
	v_mov_b64_e32 v[32:33], v[78:79]
	v_mov_b64_e32 v[52:53], v[102:103]
	v_mov_b64_e32 v[54:55], v[104:105]
	v_cndmask_b32_e64 v1, v1, v34, s[4:5]
	s_nop 0
	v_and_b32_e32 v56, 0xffff0000, v29
	v_lshlrev_b32_e32 v57, 16, v29
	v_lshlrev_b32_e32 v60, 16, v28
	v_and_b32_e32 v61, 0xffff0000, v28
	s_nop 0
	v_lshlrev_b32_e32 v28, 16, v36
	v_and_b32_e32 v29, 0xffff0000, v36
	v_and_b32_e32 v58, 0xffff0000, v37
	v_lshlrev_b32_e32 v59, 16, v37
	v_pk_mul_f32 v[62:63], v[28:29], v[28:29]
	v_pk_mul_f32 v[36:37], v[58:59], v[58:59]
	v_pk_fma_f32 v[62:63], v[60:61], v[60:61], v[62:63]
	v_pk_fma_f32 v[36:37], v[56:57], v[56:57], v[36:37]
	v_add_f32_e32 v19, v62, v63
	v_add_f32_e32 v19, v37, v19
	v_add_f32_e32 v19, v36, v19
	ds_bpermute_b32 v21, v38, v19
	s_waitcnt lgkmcnt(0)
	v_add_f32_e32 v19, v19, v21
	ds_bpermute_b32 v21, v39, v19
	s_waitcnt lgkmcnt(0)
	v_add_f32_e32 v19, v19, v21
	ds_bpermute_b32 v21, v40, v19
	s_waitcnt lgkmcnt(0)
	v_add_f32_e32 v19, v19, v21
	v_fmamk_f32 v19, v19, 0x3c800000, v49
	v_mul_f32_e32 v21, 0x4b800000, v19
	v_cmp_gt_f32_e64 s[8:9], s17, v19
	s_nop 1
	v_cndmask_b32_e64 v19, v19, v21, s[8:9]
	v_rsq_f32_e32 v19, v19
	s_nop 0
	v_mul_f32_e32 v21, 0x45800000, v19
	v_cndmask_b32_e64 v36, v19, v21, s[8:9]
	s_nop 0
	v_mul_f32_e32 v19, v32, v36
	v_pk_mul_f32 v[30:31], v[30:31], v[36:37] op_sel_hi:[1,0]
	s_nop 0
	v_pk_mul_f32 v[52:53], v[52:53], v[36:37] op_sel_hi:[1,0]
	v_mul_f32_e32 v21, v54, v36
	v_mov_b32_e32 v32, v55
	v_mul_f32_e32 v37, v19, v57
	v_mul_f32_e32 v35, v21, v59
	v_pk_mul_f32 v[32:33], v[32:33], v[36:37] op_sel_hi:[1,0]
	v_mov_b32_e32 v59, v56
	v_pk_mul_f32 v[30:31], v[30:31], v[60:61]
	v_pk_mul_f32 v[28:29], v[52:53], v[28:29]
	v_pk_mul_f32 v[32:33], v[32:33], v[58:59]
	s_and_saveexec_b64 s[8:9], s[6:7]
	s_cbranch_execz .LBB0_348
	v_mul_f32_e32 v19, v45, v1
	v_mul_f32_e32 v19, 0.15915494, v19
	v_cos_f32_e32 v52, v19
	v_sin_f32_e32 v54, v19
	v_mul_f32_e32 v19, v46, v1
	v_mul_f32_e32 v19, 0.15915494, v19
	v_mul_f32_e32 v23, v48, v1
	v_cos_f32_e32 v53, v19
	v_sin_f32_e32 v55, v19
	v_mul_f32_e32 v19, v47, v1
	v_mul_f32_e32 v23, 0.15915494, v23
	v_mul_f32_e32 v19, 0.15915494, v19
	v_cos_f32_e32 v59, v23
	v_sin_f32_e32 v58, v23
	v_cos_f32_e32 v21, v19
	v_sin_f32_e32 v19, v19
	v_pk_mul_f32 v[56:57], v[54:55], v[28:29]
	v_pk_mul_f32 v[64:65], v[58:59], v[32:33]
	v_mul_f32_e32 v34, v21, v37
	v_mul_f32_e32 v36, v19, v35
	v_mul_f32_e32 v60, v21, v35
	v_mul_f32_e32 v62, v19, v37
	v_mov_b32_e32 v35, v65
	v_mov_b32_e32 v37, v64
	v_mov_b32_e32 v64, v59
	v_mov_b32_e32 v65, v58
	v_pk_mul_f32 v[32:33], v[64:65], v[32:33]
	v_pk_mul_f32 v[54:55], v[54:55], v[30:31]
	v_mov_b32_e32 v61, v32
	v_mov_b32_e32 v63, v33
	v_pk_fma_f32 v[30:31], v[52:53], v[30:31], v[56:57] neg_lo:[0,0,1] neg_hi:[0,0,1]
	v_pk_add_f32 v[56:57], v[34:35], v[36:37] neg_lo:[0,1] neg_hi:[0,1]
	v_pk_add_f32 v[32:33], v[60:61], v[62:63]
	v_pk_fma_f32 v[28:29], v[52:53], v[28:29], v[54:55]
	v_mov_b32_e32 v35, v32
	v_mov_b32_e32 v32, v33
	v_mov_b32_e32 v37, v56
	v_mov_b32_e32 v33, v57
.LBB0_348:
	s_or_b64 exec, exec, s[8:9]
	v_mov_b32_e32 v36, v30
	v_mov_b32_e32 v30, v31
	v_mov_b32_e32 v31, v33
	v_pk_mul_f32 v[30:31], v[30:31], s[34:35] op_sel_hi:[1,0]
	v_pk_mul_f32 v[36:37], v[36:37], s[34:35] op_sel_hi:[1,0]
	v_and_b32_sdwa v23, v31, v50 dst_sel:DWORD dst_unused:UNUSED_PAD src0_sel:WORD_1 src1_sel:DWORD
	v_and_b32_sdwa v25, v30, v50 dst_sel:DWORD dst_unused:UNUSED_PAD src0_sel:WORD_1 src1_sel:DWORD
	v_and_b32_sdwa v19, v37, v50 dst_sel:DWORD dst_unused:UNUSED_PAD src0_sel:WORD_1 src1_sel:DWORD
	v_and_b32_sdwa v21, v36, v50 dst_sel:DWORD dst_unused:UNUSED_PAD src0_sel:WORD_1 src1_sel:DWORD
	v_add3_u32 v23, v31, v23, s18
	v_add3_u32 v25, v30, v25, s18
	v_mov_b32_e32 v34, v28
	v_mov_b32_e32 v28, v29
	v_mov_b32_e32 v29, v32
	v_add3_u32 v21, v36, v21, s18
	v_add3_u32 v19, v37, v19, s18
	v_and_b32_e32 v23, 0xffff0000, v23
	v_and_b32_e32 v25, 0xffff0000, v25
	v_pk_mul_f32 v[28:29], v[28:29], s[34:35] op_sel_hi:[1,0]
	v_or_b32_sdwa v31, v23, v19 dst_sel:DWORD dst_unused:UNUSED_PAD src0_sel:DWORD src1_sel:WORD_1
	v_or_b32_sdwa v30, v25, v21 dst_sel:DWORD dst_unused:UNUSED_PAD src0_sel:DWORD src1_sel:WORD_1
	v_pk_mul_f32 v[34:35], v[34:35], s[34:35] op_sel_hi:[1,0]
	v_and_b32_sdwa v23, v29, v50 dst_sel:DWORD dst_unused:UNUSED_PAD src0_sel:WORD_1 src1_sel:DWORD
	v_and_b32_sdwa v25, v28, v50 dst_sel:DWORD dst_unused:UNUSED_PAD src0_sel:WORD_1 src1_sel:DWORD
	v_and_b32_sdwa v19, v35, v50 dst_sel:DWORD dst_unused:UNUSED_PAD src0_sel:WORD_1 src1_sel:DWORD
	v_and_b32_sdwa v21, v34, v50 dst_sel:DWORD dst_unused:UNUSED_PAD src0_sel:WORD_1 src1_sel:DWORD
	v_add3_u32 v23, v29, v23, s18
	v_add3_u32 v25, v28, v25, s18
	v_add3_u32 v21, v34, v21, s18
	v_add3_u32 v19, v35, v19, s18
	v_and_b32_e32 v23, 0xffff0000, v23
	v_and_b32_e32 v25, 0xffff0000, v25
	v_or_b32_sdwa v29, v23, v19 dst_sel:DWORD dst_unused:UNUSED_PAD src0_sel:DWORD src1_sel:WORD_1
	v_or_b32_sdwa v28, v25, v21 dst_sel:DWORD dst_unused:UNUSED_PAD src0_sel:DWORD src1_sel:WORD_1
	global_store_dwordx2 v[26:27], v[30:31], off offset:832
	global_store_dwordx2 v[26:27], v[28:29], off offset:864
	v_mov_b32_e32 v28, 0
	v_mov_b32_e32 v29, 0
	v_mov_b32_e32 v32, 0
	v_mov_b32_e32 v33, 0
	v_mov_b32_e32 v30, 0
	v_mov_b32_e32 v31, 0
	v_mov_b32_e32 v34, 0
	v_mov_b32_e32 v35, 0
	s_and_saveexec_b64 s[8:9], vcc
	s_cbranch_execz .LBB0_350
	v_mov_b64_e32 v[28:29], v[150:151]
	v_mov_b64_e32 v[32:33], v[152:153]
	s_nop 0
	v_lshlrev_b32_e32 v30, 16, v28
	v_and_b32_e32 v31, 0xffff0000, v28
	v_lshlrev_b32_e32 v34, 16, v29
	v_and_b32_e32 v35, 0xffff0000, v29
	s_nop 0
	v_lshlrev_b32_e32 v28, 16, v32
	v_and_b32_e32 v29, 0xffff0000, v32
	v_lshlrev_b32_e32 v32, 16, v33
	v_and_b32_e32 v33, 0xffff0000, v33

.LBB0_354:
	s_or_b64 exec, exec, s[8:9]
	v_mov_b64_e32 v[52:53], v[146:147]
	v_mov_b64_e32 v[28:29], v[148:149]
	s_nop 0
	v_lshlrev_b32_e32 v35, 16, v53
	v_lshlrev_b32_e32 v34, 16, v52
	v_and_b32_e32 v33, 0xffff0000, v52
	s_nop 0
	v_lshlrev_b32_e32 v30, 16, v28
	v_and_b32_e32 v37, 0xffff0000, v28
	v_lshlrev_b32_e32 v31, 16, v29
	v_and_b32_e32 v29, 0xffff0000, v29
	v_and_b32_e32 v28, 0xffff0000, v53
	s_and_saveexec_b64 s[8:9], s[6:7]
	s_cbranch_execz .LBB0_356
	v_mul_f32_e32 v19, v45, v1
	v_mul_f32_e32 v19, 0.15915494, v19
	v_cos_f32_e32 v52, v19
	v_sin_f32_e32 v54, v19
	v_mul_f32_e32 v19, v46, v1
	v_mul_f32_e32 v19, 0.15915494, v19
	v_cos_f32_e32 v53, v19
	v_sin_f32_e32 v55, v19
	v_mul_f32_e32 v19, v47, v1
	v_mul_f32_e32 v23, v48, v1
	v_mul_f32_e32 v19, 0.15915494, v19
	v_mul_f32_e32 v23, 0.15915494, v23
	v_cos_f32_e32 v21, v19
	v_sin_f32_e32 v19, v19
	v_cos_f32_e32 v58, v23
	v_sin_f32_e32 v59, v23
	v_mov_b32_e32 v36, v30
	v_mov_b32_e32 v32, v34
	v_mul_f32_e32 v30, v21, v35
	v_mul_f32_e32 v64, v19, v35
	v_pk_mul_f32 v[34:35], v[58:59], v[28:29]
	v_mul_f32_e32 v60, v19, v31
	v_mul_f32_e32 v62, v21, v31
	v_mov_b32_e32 v31, v34
	v_mov_b32_e32 v61, v35
	v_mov_b32_e32 v34, v59
	v_mov_b32_e32 v35, v58
	v_pk_mul_f32 v[28:29], v[34:35], v[28:29]
	v_pk_mul_f32 v[56:57], v[54:55], v[36:37]
	v_pk_mul_f32 v[36:37], v[52:53], v[36:37]
	v_mov_b32_e32 v65, v28
	v_mov_b32_e32 v63, v29
	v_pk_fma_f32 v[34:35], v[52:53], v[32:33], v[56:57] neg_lo:[0,0,1] neg_hi:[0,0,1]
	v_pk_add_f32 v[52:53], v[30:31], v[60:61] neg_lo:[0,1] neg_hi:[0,1]
	v_pk_fma_f32 v[30:31], v[54:55], v[32:33], v[36:37]
	v_pk_add_f32 v[28:29], v[64:65], v[62:63]
	v_mov_b32_e32 v37, v31
	v_mov_b32_e32 v31, v28
	v_mov_b32_e32 v33, v35
	v_mov_b32_e32 v35, v52
	v_mov_b32_e32 v28, v53

.LBB0_359:
	v_mov_b64_e32 v[28:29], v[154:155]
	v_mov_b64_e32 v[30:31], v[156:157]
	s_nop 0
	v_lshlrev_b32_e32 v32, 16, v28
	v_and_b32_e32 v33, 0xffff0000, v28
	v_lshlrev_b32_e32 v34, 16, v29
	v_and_b32_e32 v35, 0xffff0000, v29
	s_nop 0
	v_lshlrev_b32_e32 v28, 16, v30
	v_and_b32_e32 v29, 0xffff0000, v30
	v_lshlrev_b32_e32 v30, 16, v31
	v_and_b32_e32 v31, 0xffff0000, v31
	s_or_b64 exec, exec, s[8:9]
	s_and_saveexec_b64 s[8:9], s[6:7]
	s_cbranch_execz .LBB0_358

.LBB0_797:
	v_lshl_add_u32 v150, s44, 8, v158
	s_lshl_b32 s44, s13, 10
	v_lshl_or_b32 v148, s46, 8, v160
	s_ashr_i32 s45, s44, 31
	s_cmp_lg_u32 s13, 0
	s_cselect_b64 s[46:47], -1, 0
	s_add_u32 s4, s58, s44
	s_addc_u32 s5, s59, s45
	v_mad_u32_u24 v169, v150, s94, v148
	v_lshlrev_b32_e32 v170, 11, v150
	v_lshl_add_u32 v170, v148, 1, v170
	v_mov_b32_e32 v171, v169
	global_load_dwordx2 v[174:175], v171, s[4:5]
	global_load_dwordx2 v[176:177], v171, s[4:5] offset:128
	v_add_u32_e32 v171, 0xc000, v169
	global_load_dwordx2 v[178:179], v171, s[4:5]
	global_load_dwordx2 v[180:181], v171, s[4:5] offset:128
	v_add_u32_e32 v171, 0x18000, v169
	global_load_dwordx2 v[182:183], v171, s[4:5]
	global_load_dwordx2 v[184:185], v171, s[4:5] offset:128
	v_add_u32_e32 v171, 0x24000, v169
	global_load_dwordx2 v[186:187], v171, s[4:5]
	global_load_dwordx2 v[188:189], v171, s[4:5] offset:128
	v_add_u32_e32 v171, 0x60000, v169
	global_load_dwordx2 v[190:191], v171, s[4:5]
	global_load_dwordx2 v[192:193], v171, s[4:5] offset:128
	v_add_u32_e32 v171, 0x6c000, v169
	global_load_dwordx2 v[194:195], v171, s[4:5]
	global_load_dwordx2 v[196:197], v171, s[4:5] offset:128
	v_add_u32_e32 v171, 0x78000, v169
	global_load_dwordx2 v[198:199], v171, s[4:5]
	global_load_dwordx2 v[200:201], v171, s[4:5] offset:128
	v_add_u32_e32 v171, 0x84000, v169
	global_load_dwordx2 v[202:203], v171, s[4:5]
	global_load_dwordx2 v[204:205], v171, s[4:5] offset:128
	s_cmp_eq_u32 s13, 0
	s_cbranch_scc1 .Lbra_z0
	v_mov_b32_e32 v172, v170
	global_load_dwordx4 v[206:209], v172, s[54:55]
	v_mov_b32_e32 v172, v170
	global_load_dwordx4 v[210:213], v172, s[54:55] offset:256
	v_add_u32_e32 v172, 0x8000, v170
	global_load_dwordx4 v[214:217], v172, s[54:55]
	v_add_u32_e32 v172, 0x8000, v170
	global_load_dwordx4 v[218:221], v172, s[54:55] offset:256
	v_add_u32_e32 v172, 0x10000, v170
	global_load_dwordx4 v[222:225], v172, s[54:55]
	s_waitcnt vmcnt(4)
	v_cvt_f32_ubyte0_e32 v128, v174
	v_cvt_f32_ubyte1_e32 v129, v174
	v_cvt_f32_ubyte2_e32 v130, v174
	v_cvt_f32_ubyte3_e32 v131, v174
	v_lshlrev_b32_e32 v164, 16, v206
	v_and_b32_e32 v165, 0xffff0000, v206
	v_lshlrev_b32_e32 v166, 16, v207
	v_and_b32_e32 v167, 0xffff0000, v207
	v_pk_mul_f32 v[128:129], v[128:129], s[14:15] op_sel_hi:[1,0]
	v_pk_mul_f32 v[130:131], v[130:131], s[14:15] op_sel_hi:[1,0]
	v_pk_fma_f32 v[124:125], v[124:125], v[128:129], v[164:165]
	v_pk_fma_f32 v[126:127], v[126:127], v[130:131], v[166:167]
	v_cvt_f32_ubyte0_e32 v128, v175
	v_cvt_f32_ubyte1_e32 v129, v175
	v_cvt_f32_ubyte2_e32 v130, v175
	v_cvt_f32_ubyte3_e32 v131, v175
	v_lshlrev_b32_e32 v164, 16, v208
	v_and_b32_e32 v165, 0xffff0000, v208
	v_lshlrev_b32_e32 v166, 16, v209
	v_and_b32_e32 v167, 0xffff0000, v209
	v_pk_mul_f32 v[128:129], v[128:129], s[14:15] op_sel_hi:[1,0]
	v_pk_mul_f32 v[130:131], v[130:131], s[14:15] op_sel_hi:[1,0]
	v_pk_fma_f32 v[120:121], v[120:121], v[128:129], v[164:165]
	v_pk_fma_f32 v[122:123], v[122:123], v[130:131], v[166:167]
	v_cvt_pk_bf16_f32 v124, v124, v125
	v_cvt_pk_bf16_f32 v125, v126, v127
	v_cvt_pk_bf16_f32 v126, v120, v121
	v_cvt_pk_bf16_f32 v127, v122, v123
	v_mov_b32_e32 v173, v170
	global_store_dwordx4 v173, v[124:127], s[54:55]
	v_add_u32_e32 v172, 0x10000, v170
	global_load_dwordx4 v[206:209], v172, s[54:55] offset:256
	s_waitcnt vmcnt(5)
	v_cvt_f32_ubyte0_e32 v128, v176
	v_cvt_f32_ubyte1_e32 v129, v176
	v_cvt_f32_ubyte2_e32 v130, v176
	v_cvt_f32_ubyte3_e32 v131, v176
	v_lshlrev_b32_e32 v164, 16, v210
	v_and_b32_e32 v165, 0xffff0000, v210
	v_lshlrev_b32_e32 v166, 16, v211
	v_and_b32_e32 v167, 0xffff0000, v211
	v_pk_mul_f32 v[128:129], v[128:129], s[14:15] op_sel_hi:[1,0]
	v_pk_mul_f32 v[130:131], v[130:131], s[14:15] op_sel_hi:[1,0]
	v_pk_fma_f32 v[116:117], v[116:117], v[128:129], v[164:165]
	v_pk_fma_f32 v[118:119], v[118:119], v[130:131], v[166:167]
	v_cvt_f32_ubyte0_e32 v128, v177
	v_cvt_f32_ubyte1_e32 v129, v177
	v_cvt_f32_ubyte2_e32 v130, v177
	v_cvt_f32_ubyte3_e32 v131, v177
	v_lshlrev_b32_e32 v164, 16, v212
	v_and_b32_e32 v165, 0xffff0000, v212
	v_lshlrev_b32_e32 v166, 16, v213
	v_and_b32_e32 v167, 0xffff0000, v213
	v_pk_mul_f32 v[128:129], v[128:129], s[14:15] op_sel_hi:[1,0]
	v_pk_mul_f32 v[130:131], v[130:131], s[14:15] op_sel_hi:[1,0]
	v_pk_fma_f32 v[112:113], v[112:113], v[128:129], v[164:165]
	v_pk_fma_f32 v[114:115], v[114:115], v[130:131], v[166:167]
	v_cvt_pk_bf16_f32 v116, v116, v117
	v_cvt_pk_bf16_f32 v117, v118, v119
	v_cvt_pk_bf16_f32 v118, v112, v113
	v_cvt_pk_bf16_f32 v119, v114, v115
	v_mov_b32_e32 v173, v170
	global_store_dwordx4 v173, v[116:119], s[54:55] offset:256
	v_add_u32_e32 v172, 0x18000, v170
	global_load_dwordx4 v[210:213], v172, s[54:55]
	s_waitcnt vmcnt(6)
	v_cvt_f32_ubyte0_e32 v128, v178
	v_cvt_f32_ubyte1_e32 v129, v178
	v_cvt_f32_ubyte2_e32 v130, v178
	v_cvt_f32_ubyte3_e32 v131, v178
	v_lshlrev_b32_e32 v164, 16, v214
	v_and_b32_e32 v165, 0xffff0000, v214
	v_lshlrev_b32_e32 v166, 16, v215
	v_and_b32_e32 v167, 0xffff0000, v215
	v_pk_mul_f32 v[128:129], v[128:129], s[14:15] op_sel_hi:[1,0]
	v_pk_mul_f32 v[130:131], v[130:131], s[14:15] op_sel_hi:[1,0]
	v_pk_fma_f32 v[108:109], v[108:109], v[128:129], v[164:165]
	v_pk_fma_f32 v[110:111], v[110:111], v[130:131], v[166:167]
	v_cvt_f32_ubyte0_e32 v128, v179
	v_cvt_f32_ubyte1_e32 v129, v179
	v_cvt_f32_ubyte2_e32 v130, v179
	v_cvt_f32_ubyte3_e32 v131, v179
	v_lshlrev_b32_e32 v164, 16, v216
	v_and_b32_e32 v165, 0xffff0000, v216
	v_lshlrev_b32_e32 v166, 16, v217
	v_and_b32_e32 v167, 0xffff0000, v217
	v_pk_mul_f32 v[128:129], v[128:129], s[14:15] op_sel_hi:[1,0]
	v_pk_mul_f32 v[130:131], v[130:131], s[14:15] op_sel_hi:[1,0]
	v_pk_fma_f32 v[104:105], v[104:105], v[128:129], v[164:165]
	v_pk_fma_f32 v[106:107], v[106:107], v[130:131], v[166:167]
	v_cvt_pk_bf16_f32 v108, v108, v109
	v_cvt_pk_bf16_f32 v109, v110, v111
	v_cvt_pk_bf16_f32 v110, v104, v105
	v_cvt_pk_bf16_f32 v111, v106, v107
	v_add_u32_e32 v173, 0x8000, v170
	global_store_dwordx4 v173, v[108:111], s[54:55]
	v_add_u32_e32 v172, 0x18000, v170
	global_load_dwordx4 v[214:217], v172, s[54:55] offset:256
	s_waitcnt vmcnt(7)
	v_cvt_f32_ubyte0_e32 v128, v180
	v_cvt_f32_ubyte1_e32 v129, v180
	v_cvt_f32_ubyte2_e32 v130, v180
	v_cvt_f32_ubyte3_e32 v131, v180
	v_lshlrev_b32_e32 v164, 16, v218
	v_and_b32_e32 v165, 0xffff0000, v218
	v_lshlrev_b32_e32 v166, 16, v219
	v_and_b32_e32 v167, 0xffff0000, v219
	v_pk_mul_f32 v[128:129], v[128:129], s[14:15] op_sel_hi:[1,0]
	v_pk_mul_f32 v[130:131], v[130:131], s[14:15] op_sel_hi:[1,0]
	v_pk_fma_f32 v[100:101], v[100:101], v[128:129], v[164:165]
	v_pk_fma_f32 v[102:103], v[102:103], v[130:131], v[166:167]
	v_cvt_f32_ubyte0_e32 v128, v181
	v_cvt_f32_ubyte1_e32 v129, v181
	v_cvt_f32_ubyte2_e32 v130, v181
	v_cvt_f32_ubyte3_e32 v131, v181
	v_lshlrev_b32_e32 v164, 16, v220
	v_and_b32_e32 v165, 0xffff0000, v220
	v_lshlrev_b32_e32 v166, 16, v221
	v_and_b32_e32 v167, 0xffff0000, v221
	v_pk_mul_f32 v[128:129], v[128:129], s[14:15] op_sel_hi:[1,0]
	v_pk_mul_f32 v[130:131], v[130:131], s[14:15] op_sel_hi:[1,0]
	v_pk_fma_f32 v[96:97], v[96:97], v[128:129], v[164:165]
	v_pk_fma_f32 v[98:99], v[98:99], v[130:131], v[166:167]
	v_cvt_pk_bf16_f32 v100, v100, v101
	v_cvt_pk_bf16_f32 v101, v102, v103
	v_cvt_pk_bf16_f32 v102, v96, v97
	v_cvt_pk_bf16_f32 v103, v98, v99
	v_add_u32_e32 v173, 0x8000, v170
	global_store_dwordx4 v173, v[100:103], s[54:55] offset:256
	v_add_u32_e32 v172, 0x40000, v170
	global_load_dwordx4 v[218:221], v172, s[54:55]
	s_waitcnt vmcnt(8)
	v_cvt_f32_ubyte0_e32 v128, v182
	v_cvt_f32_ubyte1_e32 v129, v182
	v_cvt_f32_ubyte2_e32 v130, v182
	v_cvt_f32_ubyte3_e32 v131, v182
	v_lshlrev_b32_e32 v164, 16, v222
	v_and_b32_e32 v165, 0xffff0000, v222
	v_lshlrev_b32_e32 v166, 16, v223
	v_and_b32_e32 v167, 0xffff0000, v223
	v_pk_mul_f32 v[128:129], v[128:129], s[14:15] op_sel_hi:[1,0]
	v_pk_mul_f32 v[130:131], v[130:131], s[14:15] op_sel_hi:[1,0]
	v_pk_fma_f32 v[92:93], v[92:93], v[128:129], v[164:165]
	v_pk_fma_f32 v[94:95], v[94:95], v[130:131], v[166:167]
	v_cvt_f32_ubyte0_e32 v128, v183
	v_cvt_f32_ubyte1_e32 v129, v183
	v_cvt_f32_ubyte2_e32 v130, v183
	v_cvt_f32_ubyte3_e32 v131, v183
	v_lshlrev_b32_e32 v164, 16, v224
	v_and_b32_e32 v165, 0xffff0000, v224
	v_lshlrev_b32_e32 v166, 16, v225
	v_and_b32_e32 v167, 0xffff0000, v225
	v_pk_mul_f32 v[128:129], v[128:129], s[14:15] op_sel_hi:[1,0]
	v_pk_mul_f32 v[130:131], v[130:131], s[14:15] op_sel_hi:[1,0]
	v_pk_fma_f32 v[88:89], v[88:89], v[128:129], v[164:165]
	v_pk_fma_f32 v[90:91], v[90:91], v[130:131], v[166:167]
	v_cvt_pk_bf16_f32 v92, v92, v93
	v_cvt_pk_bf16_f32 v93, v94, v95
	v_cvt_pk_bf16_f32 v94, v88, v89
	v_cvt_pk_bf16_f32 v95, v90, v91
	v_add_u32_e32 v173, 0x10000, v170
	global_store_dwordx4 v173, v[92:95], s[54:55]
	v_add_u32_e32 v172, 0x40000, v170
	global_load_dwordx4 v[222:225], v172, s[54:55] offset:256
	s_waitcnt vmcnt(8)
	v_cvt_f32_ubyte0_e32 v128, v184
	v_cvt_f32_ubyte1_e32 v129, v184
	v_cvt_f32_ubyte2_e32 v130, v184
	v_cvt_f32_ubyte3_e32 v131, v184
	v_lshlrev_b32_e32 v164, 16, v206
	v_and_b32_e32 v165, 0xffff0000, v206
	v_lshlrev_b32_e32 v166, 16, v207
	v_and_b32_e32 v167, 0xffff0000, v207
	v_pk_mul_f32 v[128:129], v[128:129], s[14:15] op_sel_hi:[1,0]
	v_pk_mul_f32 v[130:131], v[130:131], s[14:15] op_sel_hi:[1,0]
	v_pk_fma_f32 v[84:85], v[84:85], v[128:129], v[164:165]
	v_pk_fma_f32 v[86:87], v[86:87], v[130:131], v[166:167]
	v_cvt_f32_ubyte0_e32 v128, v185
	v_cvt_f32_ubyte1_e32 v129, v185
	v_cvt_f32_ubyte2_e32 v130, v185
	v_cvt_f32_ubyte3_e32 v131, v185
	v_lshlrev_b32_e32 v164, 16, v208
	v_and_b32_e32 v165, 0xffff0000, v208
	v_lshlrev_b32_e32 v166, 16, v209
	v_and_b32_e32 v167, 0xffff0000, v209
	v_pk_mul_f32 v[128:129], v[128:129], s[14:15] op_sel_hi:[1,0]
	v_pk_mul_f32 v[130:131], v[130:131], s[14:15] op_sel_hi:[1,0]
	v_pk_fma_f32 v[80:81], v[80:81], v[128:129], v[164:165]
	v_pk_fma_f32 v[82:83], v[82:83], v[130:131], v[166:167]
	v_cvt_pk_bf16_f32 v84, v84, v85
	v_cvt_pk_bf16_f32 v85, v86, v87
	v_cvt_pk_bf16_f32 v86, v80, v81
	v_cvt_pk_bf16_f32 v87, v82, v83
	v_add_u32_e32 v173, 0x10000, v170
	global_store_dwordx4 v173, v[84:87], s[54:55] offset:256
	v_add_u32_e32 v172, 0x48000, v170
	global_load_dwordx4 v[206:209], v172, s[54:55]
	s_waitcnt vmcnt(8)
	v_cvt_f32_ubyte0_e32 v128, v186
	v_cvt_f32_ubyte1_e32 v129, v186
	v_cvt_f32_ubyte2_e32 v130, v186
	v_cvt_f32_ubyte3_e32 v131, v186
	v_lshlrev_b32_e32 v164, 16, v210
	v_and_b32_e32 v165, 0xffff0000, v210
	v_lshlrev_b32_e32 v166, 16, v211
	v_and_b32_e32 v167, 0xffff0000, v211
	v_pk_mul_f32 v[128:129], v[128:129], s[14:15] op_sel_hi:[1,0]
	v_pk_mul_f32 v[130:131], v[130:131], s[14:15] op_sel_hi:[1,0]
	v_pk_fma_f32 v[76:77], v[76:77], v[128:129], v[164:165]
	v_pk_fma_f32 v[78:79], v[78:79], v[130:131], v[166:167]
	v_cvt_f32_ubyte0_e32 v128, v187
	v_cvt_f32_ubyte1_e32 v129, v187
	v_cvt_f32_ubyte2_e32 v130, v187
	v_cvt_f32_ubyte3_e32 v131, v187
	v_lshlrev_b32_e32 v164, 16, v212
	v_and_b32_e32 v165, 0xffff0000, v212
	v_lshlrev_b32_e32 v166, 16, v213
	v_and_b32_e32 v167, 0xffff0000, v213
	v_pk_mul_f32 v[128:129], v[128:129], s[14:15] op_sel_hi:[1,0]
	v_pk_mul_f32 v[130:131], v[130:131], s[14:15] op_sel_hi:[1,0]
	v_pk_fma_f32 v[72:73], v[72:73], v[128:129], v[164:165]
	v_pk_fma_f32 v[74:75], v[74:75], v[130:131], v[166:167]
	v_cvt_pk_bf16_f32 v76, v76, v77
	v_cvt_pk_bf16_f32 v77, v78, v79
	v_cvt_pk_bf16_f32 v78, v72, v73
	v_cvt_pk_bf16_f32 v79, v74, v75
	v_add_u32_e32 v173, 0x18000, v170
	global_store_dwordx4 v173, v[76:79], s[54:55]
	v_add_u32_e32 v172, 0x48000, v170
	global_load_dwordx4 v[210:213], v172, s[54:55] offset:256
	s_waitcnt vmcnt(8)
	v_cvt_f32_ubyte0_e32 v128, v188
	v_cvt_f32_ubyte1_e32 v129, v188
	v_cvt_f32_ubyte2_e32 v130, v188
	v_cvt_f32_ubyte3_e32 v131, v188
	v_lshlrev_b32_e32 v164, 16, v214
	v_and_b32_e32 v165, 0xffff0000, v214
	v_lshlrev_b32_e32 v166, 16, v215
	v_and_b32_e32 v167, 0xffff0000, v215
	v_pk_mul_f32 v[128:129], v[128:129], s[14:15] op_sel_hi:[1,0]
	v_pk_mul_f32 v[130:131], v[130:131], s[14:15] op_sel_hi:[1,0]
	v_pk_fma_f32 v[68:69], v[68:69], v[128:129], v[164:165]
	v_pk_fma_f32 v[70:71], v[70:71], v[130:131], v[166:167]
	v_cvt_f32_ubyte0_e32 v128, v189
	v_cvt_f32_ubyte1_e32 v129, v189
	v_cvt_f32_ubyte2_e32 v130, v189
	v_cvt_f32_ubyte3_e32 v131, v189
	v_lshlrev_b32_e32 v164, 16, v216
	v_and_b32_e32 v165, 0xffff0000, v216
	v_lshlrev_b32_e32 v166, 16, v217
	v_and_b32_e32 v167, 0xffff0000, v217
	v_pk_mul_f32 v[128:129], v[128:129], s[14:15] op_sel_hi:[1,0]
	v_pk_mul_f32 v[130:131], v[130:131], s[14:15] op_sel_hi:[1,0]
	v_pk_fma_f32 v[64:65], v[64:65], v[128:129], v[164:165]
	v_pk_fma_f32 v[66:67], v[66:67], v[130:131], v[166:167]
	v_cvt_pk_bf16_f32 v68, v68, v69
	v_cvt_pk_bf16_f32 v69, v70, v71
	v_cvt_pk_bf16_f32 v70, v64, v65
	v_cvt_pk_bf16_f32 v71, v66, v67
	v_add_u32_e32 v173, 0x18000, v170
	global_store_dwordx4 v173, v[68:71], s[54:55] offset:256
	v_add_u32_e32 v172, 0x50000, v170
	global_load_dwordx4 v[214:217], v172, s[54:55]
	s_waitcnt vmcnt(8)
	v_cvt_f32_ubyte0_e32 v128, v190
	v_cvt_f32_ubyte1_e32 v129, v190
	v_cvt_f32_ubyte2_e32 v130, v190
	v_cvt_f32_ubyte3_e32 v131, v190
	v_lshlrev_b32_e32 v164, 16, v218
	v_and_b32_e32 v165, 0xffff0000, v218
	v_lshlrev_b32_e32 v166, 16, v219
	v_and_b32_e32 v167, 0xffff0000, v219
	v_pk_mul_f32 v[128:129], v[128:129], s[14:15] op_sel_hi:[1,0]
	v_pk_mul_f32 v[130:131], v[130:131], s[14:15] op_sel_hi:[1,0]
	v_pk_fma_f32 v[60:61], v[60:61], v[128:129], v[164:165]
	v_pk_fma_f32 v[62:63], v[62:63], v[130:131], v[166:167]
	v_cvt_f32_ubyte0_e32 v128, v191
	v_cvt_f32_ubyte1_e32 v129, v191
	v_cvt_f32_ubyte2_e32 v130, v191
	v_cvt_f32_ubyte3_e32 v131, v191
	v_lshlrev_b32_e32 v164, 16, v220
	v_and_b32_e32 v165, 0xffff0000, v220
	v_lshlrev_b32_e32 v166, 16, v221
	v_and_b32_e32 v167, 0xffff0000, v221
	v_pk_mul_f32 v[128:129], v[128:129], s[14:15] op_sel_hi:[1,0]
	v_pk_mul_f32 v[130:131], v[130:131], s[14:15] op_sel_hi:[1,0]
	v_pk_fma_f32 v[56:57], v[56:57], v[128:129], v[164:165]
	v_pk_fma_f32 v[58:59], v[58:59], v[130:131], v[166:167]
	v_cvt_pk_bf16_f32 v60, v60, v61
	v_cvt_pk_bf16_f32 v61, v62, v63
	v_cvt_pk_bf16_f32 v62, v56, v57
	v_cvt_pk_bf16_f32 v63, v58, v59
	v_add_u32_e32 v173, 0x40000, v170
	global_store_dwordx4 v173, v[60:63], s[54:55]
	v_add_u32_e32 v172, 0x50000, v170
	global_load_dwordx4 v[218:221], v172, s[54:55] offset:256
	s_waitcnt vmcnt(8)
	v_cvt_f32_ubyte0_e32 v128, v192
	v_cvt_f32_ubyte1_e32 v129, v192
	v_cvt_f32_ubyte2_e32 v130, v192
	v_cvt_f32_ubyte3_e32 v131, v192
	v_lshlrev_b32_e32 v164, 16, v222
	v_and_b32_e32 v165, 0xffff0000, v222
	v_lshlrev_b32_e32 v166, 16, v223
	v_and_b32_e32 v167, 0xffff0000, v223
	v_pk_mul_f32 v[128:129], v[128:129], s[14:15] op_sel_hi:[1,0]
	v_pk_mul_f32 v[130:131], v[130:131], s[14:15] op_sel_hi:[1,0]
	v_pk_fma_f32 v[52:53], v[52:53], v[128:129], v[164:165]
	v_pk_fma_f32 v[54:55], v[54:55], v[130:131], v[166:167]
	v_cvt_f32_ubyte0_e32 v128, v193
	v_cvt_f32_ubyte1_e32 v129, v193
	v_cvt_f32_ubyte2_e32 v130, v193
	v_cvt_f32_ubyte3_e32 v131, v193
	v_lshlrev_b32_e32 v164, 16, v224
	v_and_b32_e32 v165, 0xffff0000, v224
	v_lshlrev_b32_e32 v166, 16, v225
	v_and_b32_e32 v167, 0xffff0000, v225
	v_pk_mul_f32 v[128:129], v[128:129], s[14:15] op_sel_hi:[1,0]
	v_pk_mul_f32 v[130:131], v[130:131], s[14:15] op_sel_hi:[1,0]
	v_pk_fma_f32 v[48:49], v[48:49], v[128:129], v[164:165]
	v_pk_fma_f32 v[50:51], v[50:51], v[130:131], v[166:167]
	v_cvt_pk_bf16_f32 v52, v52, v53
	v_cvt_pk_bf16_f32 v53, v54, v55
	v_cvt_pk_bf16_f32 v54, v48, v49
	v_cvt_pk_bf16_f32 v55, v50, v51
	v_add_u32_e32 v173, 0x40000, v170
	global_store_dwordx4 v173, v[52:55], s[54:55] offset:256
	v_add_u32_e32 v172, 0x58000, v170
	global_load_dwordx4 v[222:225], v172, s[54:55]
	s_waitcnt vmcnt(8)
	v_cvt_f32_ubyte0_e32 v128, v194
	v_cvt_f32_ubyte1_e32 v129, v194
	v_cvt_f32_ubyte2_e32 v130, v194
	v_cvt_f32_ubyte3_e32 v131, v194
	v_lshlrev_b32_e32 v164, 16, v206
	v_and_b32_e32 v165, 0xffff0000, v206
	v_lshlrev_b32_e32 v166, 16, v207
	v_and_b32_e32 v167, 0xffff0000, v207
	v_pk_mul_f32 v[128:129], v[128:129], s[14:15] op_sel_hi:[1,0]
	v_pk_mul_f32 v[130:131], v[130:131], s[14:15] op_sel_hi:[1,0]
	v_pk_fma_f32 v[44:45], v[44:45], v[128:129], v[164:165]
	v_pk_fma_f32 v[46:47], v[46:47], v[130:131], v[166:167]
	v_cvt_f32_ubyte0_e32 v128, v195
	v_cvt_f32_ubyte1_e32 v129, v195
	v_cvt_f32_ubyte2_e32 v130, v195
	v_cvt_f32_ubyte3_e32 v131, v195
	v_lshlrev_b32_e32 v164, 16, v208
	v_and_b32_e32 v165, 0xffff0000, v208
	v_lshlrev_b32_e32 v166, 16, v209
	v_and_b32_e32 v167, 0xffff0000, v209
	v_pk_mul_f32 v[128:129], v[128:129], s[14:15] op_sel_hi:[1,0]
	v_pk_mul_f32 v[130:131], v[130:131], s[14:15] op_sel_hi:[1,0]
	v_pk_fma_f32 v[40:41], v[40:41], v[128:129], v[164:165]
	v_pk_fma_f32 v[42:43], v[42:43], v[130:131], v[166:167]
	v_cvt_pk_bf16_f32 v44, v44, v45
	v_cvt_pk_bf16_f32 v45, v46, v47
	v_cvt_pk_bf16_f32 v46, v40, v41
	v_cvt_pk_bf16_f32 v47, v42, v43
	v_add_u32_e32 v173, 0x48000, v170
	global_store_dwordx4 v173, v[44:47], s[54:55]
	v_add_u32_e32 v172, 0x58000, v170
	global_load_dwordx4 v[206:209], v172, s[54:55] offset:256
	s_waitcnt vmcnt(8)
	v_cvt_f32_ubyte0_e32 v128, v196
	v_cvt_f32_ubyte1_e32 v129, v196
	v_cvt_f32_ubyte2_e32 v130, v196
	v_cvt_f32_ubyte3_e32 v131, v196
	v_lshlrev_b32_e32 v164, 16, v210
	v_and_b32_e32 v165, 0xffff0000, v210
	v_lshlrev_b32_e32 v166, 16, v211
	v_and_b32_e32 v167, 0xffff0000, v211
	v_pk_mul_f32 v[128:129], v[128:129], s[14:15] op_sel_hi:[1,0]
	v_pk_mul_f32 v[130:131], v[130:131], s[14:15] op_sel_hi:[1,0]
	v_pk_fma_f32 v[36:37], v[36:37], v[128:129], v[164:165]
	v_pk_fma_f32 v[38:39], v[38:39], v[130:131], v[166:167]
	v_cvt_f32_ubyte0_e32 v128, v197
	v_cvt_f32_ubyte1_e32 v129, v197
	v_cvt_f32_ubyte2_e32 v130, v197
	v_cvt_f32_ubyte3_e32 v131, v197
	v_lshlrev_b32_e32 v164, 16, v212
	v_and_b32_e32 v165, 0xffff0000, v212
	v_lshlrev_b32_e32 v166, 16, v213
	v_and_b32_e32 v167, 0xffff0000, v213
	v_pk_mul_f32 v[128:129], v[128:129], s[14:15] op_sel_hi:[1,0]
	v_pk_mul_f32 v[130:131], v[130:131], s[14:15] op_sel_hi:[1,0]
	v_pk_fma_f32 v[32:33], v[32:33], v[128:129], v[164:165]
	v_pk_fma_f32 v[34:35], v[34:35], v[130:131], v[166:167]
	v_cvt_pk_bf16_f32 v36, v36, v37
	v_cvt_pk_bf16_f32 v37, v38, v39
	v_cvt_pk_bf16_f32 v38, v32, v33
	v_cvt_pk_bf16_f32 v39, v34, v35
	v_add_u32_e32 v173, 0x48000, v170
	global_store_dwordx4 v173, v[36:39], s[54:55] offset:256
	s_waitcnt vmcnt(7)
	v_cvt_f32_ubyte0_e32 v128, v198
	v_cvt_f32_ubyte1_e32 v129, v198
	v_cvt_f32_ubyte2_e32 v130, v198
	v_cvt_f32_ubyte3_e32 v131, v198
	v_lshlrev_b32_e32 v164, 16, v214
	v_and_b32_e32 v165, 0xffff0000, v214
	v_lshlrev_b32_e32 v166, 16, v215
	v_and_b32_e32 v167, 0xffff0000, v215
	v_pk_mul_f32 v[128:129], v[128:129], s[14:15] op_sel_hi:[1,0]
	v_pk_mul_f32 v[130:131], v[130:131], s[14:15] op_sel_hi:[1,0]
	v_pk_fma_f32 v[28:29], v[28:29], v[128:129], v[164:165]
	v_pk_fma_f32 v[30:31], v[30:31], v[130:131], v[166:167]
	v_cvt_f32_ubyte0_e32 v128, v199
	v_cvt_f32_ubyte1_e32 v129, v199
	v_cvt_f32_ubyte2_e32 v130, v199
	v_cvt_f32_ubyte3_e32 v131, v199
	v_lshlrev_b32_e32 v164, 16, v216
	v_and_b32_e32 v165, 0xffff0000, v216
	v_lshlrev_b32_e32 v166, 16, v217
	v_and_b32_e32 v167, 0xffff0000, v217
	v_pk_mul_f32 v[128:129], v[128:129], s[14:15] op_sel_hi:[1,0]
	v_pk_mul_f32 v[130:131], v[130:131], s[14:15] op_sel_hi:[1,0]
	v_pk_fma_f32 v[24:25], v[24:25], v[128:129], v[164:165]
	v_pk_fma_f32 v[26:27], v[26:27], v[130:131], v[166:167]
	v_cvt_pk_bf16_f32 v28, v28, v29
	v_cvt_pk_bf16_f32 v29, v30, v31
	v_cvt_pk_bf16_f32 v30, v24, v25
	v_cvt_pk_bf16_f32 v31, v26, v27
	v_add_u32_e32 v173, 0x50000, v170
	global_store_dwordx4 v173, v[28:31], s[54:55]
	s_waitcnt vmcnt(6)
	v_cvt_f32_ubyte0_e32 v128, v200
	v_cvt_f32_ubyte1_e32 v129, v200
	v_cvt_f32_ubyte2_e32 v130, v200
	v_cvt_f32_ubyte3_e32 v131, v200
	v_lshlrev_b32_e32 v164, 16, v218
	v_and_b32_e32 v165, 0xffff0000, v218
	v_lshlrev_b32_e32 v166, 16, v219
	v_and_b32_e32 v167, 0xffff0000, v219
	v_pk_mul_f32 v[128:129], v[128:129], s[14:15] op_sel_hi:[1,0]
	v_pk_mul_f32 v[130:131], v[130:131], s[14:15] op_sel_hi:[1,0]
	v_pk_fma_f32 v[20:21], v[20:21], v[128:129], v[164:165]
	v_pk_fma_f32 v[22:23], v[22:23], v[130:131], v[166:167]
	v_cvt_f32_ubyte0_e32 v128, v201
	v_cvt_f32_ubyte1_e32 v129, v201
	v_cvt_f32_ubyte2_e32 v130, v201
	v_cvt_f32_ubyte3_e32 v131, v201
	v_lshlrev_b32_e32 v164, 16, v220
	v_and_b32_e32 v165, 0xffff0000, v220
	v_lshlrev_b32_e32 v166, 16, v221
	v_and_b32_e32 v167, 0xffff0000, v221
	v_pk_mul_f32 v[128:129], v[128:129], s[14:15] op_sel_hi:[1,0]
	v_pk_mul_f32 v[130:131], v[130:131], s[14:15] op_sel_hi:[1,0]
	v_pk_fma_f32 v[16:17], v[16:17], v[128:129], v[164:165]
	v_pk_fma_f32 v[18:19], v[18:19], v[130:131], v[166:167]
	v_cvt_pk_bf16_f32 v20, v20, v21
	v_cvt_pk_bf16_f32 v21, v22, v23
	v_cvt_pk_bf16_f32 v22, v16, v17
	v_cvt_pk_bf16_f32 v23, v18, v19
	v_add_u32_e32 v173, 0x50000, v170
	global_store_dwordx4 v173, v[20:23], s[54:55] offset:256
	s_waitcnt vmcnt(5)
	v_cvt_f32_ubyte0_e32 v128, v202
	v_cvt_f32_ubyte1_e32 v129, v202
	v_cvt_f32_ubyte2_e32 v130, v202
	v_cvt_f32_ubyte3_e32 v131, v202
	v_lshlrev_b32_e32 v164, 16, v222
	v_and_b32_e32 v165, 0xffff0000, v222
	v_lshlrev_b32_e32 v166, 16, v223
	v_and_b32_e32 v167, 0xffff0000, v223
	v_pk_mul_f32 v[128:129], v[128:129], s[14:15] op_sel_hi:[1,0]
	v_pk_mul_f32 v[130:131], v[130:131], s[14:15] op_sel_hi:[1,0]
	v_pk_fma_f32 v[12:13], v[12:13], v[128:129], v[164:165]
	v_pk_fma_f32 v[14:15], v[14:15], v[130:131], v[166:167]
	v_cvt_f32_ubyte0_e32 v128, v203
	v_cvt_f32_ubyte1_e32 v129, v203
	v_cvt_f32_ubyte2_e32 v130, v203
	v_cvt_f32_ubyte3_e32 v131, v203
	v_lshlrev_b32_e32 v164, 16, v224
	v_and_b32_e32 v165, 0xffff0000, v224
	v_lshlrev_b32_e32 v166, 16, v225
	v_and_b32_e32 v167, 0xffff0000, v225
	v_pk_mul_f32 v[128:129], v[128:129], s[14:15] op_sel_hi:[1,0]
	v_pk_mul_f32 v[130:131], v[130:131], s[14:15] op_sel_hi:[1,0]
	v_pk_fma_f32 v[8:9], v[8:9], v[128:129], v[164:165]
	v_pk_fma_f32 v[10:11], v[10:11], v[130:131], v[166:167]
	v_cvt_pk_bf16_f32 v12, v12, v13
	v_cvt_pk_bf16_f32 v13, v14, v15
	v_cvt_pk_bf16_f32 v14, v8, v9
	v_cvt_pk_bf16_f32 v15, v10, v11
	v_add_u32_e32 v173, 0x58000, v170
	global_store_dwordx4 v173, v[12:15], s[54:55]
	s_waitcnt vmcnt(4)
	v_cvt_f32_ubyte0_e32 v128, v204
	v_cvt_f32_ubyte1_e32 v129, v204
	v_cvt_f32_ubyte2_e32 v130, v204
	v_cvt_f32_ubyte3_e32 v131, v204
	v_lshlrev_b32_e32 v164, 16, v206
	v_and_b32_e32 v165, 0xffff0000, v206
	v_lshlrev_b32_e32 v166, 16, v207
	v_and_b32_e32 v167, 0xffff0000, v207
	v_pk_mul_f32 v[128:129], v[128:129], s[14:15] op_sel_hi:[1,0]
	v_pk_mul_f32 v[130:131], v[130:131], s[14:15] op_sel_hi:[1,0]
	v_pk_fma_f32 v[4:5], v[4:5], v[128:129], v[164:165]
	v_pk_fma_f32 v[6:7], v[6:7], v[130:131], v[166:167]
	v_cvt_f32_ubyte0_e32 v128, v205
	v_cvt_f32_ubyte1_e32 v129, v205
	v_cvt_f32_ubyte2_e32 v130, v205
	v_cvt_f32_ubyte3_e32 v131, v205
	v_lshlrev_b32_e32 v164, 16, v208
	v_and_b32_e32 v165, 0xffff0000, v208
	v_lshlrev_b32_e32 v166, 16, v209
	v_and_b32_e32 v167, 0xffff0000, v209
	v_pk_mul_f32 v[128:129], v[128:129], s[14:15] op_sel_hi:[1,0]
	v_pk_mul_f32 v[130:131], v[130:131], s[14:15] op_sel_hi:[1,0]
	v_pk_fma_f32 v[0:1], v[0:1], v[128:129], v[164:165]
	v_pk_fma_f32 v[2:3], v[2:3], v[130:131], v[166:167]
	v_cvt_pk_bf16_f32 v4, v4, v5
	v_cvt_pk_bf16_f32 v5, v6, v7
	v_cvt_pk_bf16_f32 v6, v0, v1
	v_cvt_pk_bf16_f32 v7, v2, v3
	v_add_u32_e32 v173, 0x58000, v170
	global_store_dwordx4 v173, v[4:7], s[54:55] offset:256
	s_branch .Lbra_end
.Lbra_z0:
	v_mov_b32_e32 v154, 0
	v_mov_b32_e32 v155, 0
	s_waitcnt vmcnt(0)
	v_cvt_f32_ubyte0_e32 v128, v174
	v_cvt_f32_ubyte1_e32 v129, v174
	v_cvt_f32_ubyte2_e32 v130, v174
	v_cvt_f32_ubyte3_e32 v131, v174
	v_pk_mul_f32 v[128:129], v[128:129], s[14:15] op_sel_hi:[1,0]
	v_pk_mul_f32 v[130:131], v[130:131], s[14:15] op_sel_hi:[1,0]
	v_pk_fma_f32 v[124:125], v[124:125], v[128:129], v[154:155]
	v_pk_fma_f32 v[126:127], v[126:127], v[130:131], v[154:155]
	v_cvt_f32_ubyte0_e32 v128, v175
	v_cvt_f32_ubyte1_e32 v129, v175
	v_cvt_f32_ubyte2_e32 v130, v175
	v_cvt_f32_ubyte3_e32 v131, v175
	v_pk_mul_f32 v[128:129], v[128:129], s[14:15] op_sel_hi:[1,0]
	v_pk_mul_f32 v[130:131], v[130:131], s[14:15] op_sel_hi:[1,0]
	v_pk_fma_f32 v[120:121], v[120:121], v[128:129], v[154:155]
	v_pk_fma_f32 v[122:123], v[122:123], v[130:131], v[154:155]
	v_cvt_pk_bf16_f32 v124, v124, v125
	v_cvt_pk_bf16_f32 v125, v126, v127
	v_cvt_pk_bf16_f32 v126, v120, v121
	v_cvt_pk_bf16_f32 v127, v122, v123
	v_mov_b32_e32 v173, v170
	global_store_dwordx4 v173, v[124:127], s[54:55]
	v_cvt_f32_ubyte0_e32 v128, v176
	v_cvt_f32_ubyte1_e32 v129, v176
	v_cvt_f32_ubyte2_e32 v130, v176
	v_cvt_f32_ubyte3_e32 v131, v176
	v_pk_mul_f32 v[128:129], v[128:129], s[14:15] op_sel_hi:[1,0]
	v_pk_mul_f32 v[130:131], v[130:131], s[14:15] op_sel_hi:[1,0]
	v_pk_fma_f32 v[116:117], v[116:117], v[128:129], v[154:155]
	v_pk_fma_f32 v[118:119], v[118:119], v[130:131], v[154:155]
	v_cvt_f32_ubyte0_e32 v128, v177
	v_cvt_f32_ubyte1_e32 v129, v177
	v_cvt_f32_ubyte2_e32 v130, v177
	v_cvt_f32_ubyte3_e32 v131, v177
	v_pk_mul_f32 v[128:129], v[128:129], s[14:15] op_sel_hi:[1,0]
	v_pk_mul_f32 v[130:131], v[130:131], s[14:15] op_sel_hi:[1,0]
	v_pk_fma_f32 v[112:113], v[112:113], v[128:129], v[154:155]
	v_pk_fma_f32 v[114:115], v[114:115], v[130:131], v[154:155]
	v_cvt_pk_bf16_f32 v116, v116, v117
	v_cvt_pk_bf16_f32 v117, v118, v119
	v_cvt_pk_bf16_f32 v118, v112, v113
	v_cvt_pk_bf16_f32 v119, v114, v115
	v_mov_b32_e32 v173, v170
	global_store_dwordx4 v173, v[116:119], s[54:55] offset:256
	v_cvt_f32_ubyte0_e32 v128, v178
	v_cvt_f32_ubyte1_e32 v129, v178
	v_cvt_f32_ubyte2_e32 v130, v178
	v_cvt_f32_ubyte3_e32 v131, v178
	v_pk_mul_f32 v[128:129], v[128:129], s[14:15] op_sel_hi:[1,0]
	v_pk_mul_f32 v[130:131], v[130:131], s[14:15] op_sel_hi:[1,0]
	v_pk_fma_f32 v[108:109], v[108:109], v[128:129], v[154:155]
	v_pk_fma_f32 v[110:111], v[110:111], v[130:131], v[154:155]
	v_cvt_f32_ubyte0_e32 v128, v179
	v_cvt_f32_ubyte1_e32 v129, v179
	v_cvt_f32_ubyte2_e32 v130, v179
	v_cvt_f32_ubyte3_e32 v131, v179
	v_pk_mul_f32 v[128:129], v[128:129], s[14:15] op_sel_hi:[1,0]
	v_pk_mul_f32 v[130:131], v[130:131], s[14:15] op_sel_hi:[1,0]
	v_pk_fma_f32 v[104:105], v[104:105], v[128:129], v[154:155]
	v_pk_fma_f32 v[106:107], v[106:107], v[130:131], v[154:155]
	v_cvt_pk_bf16_f32 v108, v108, v109
	v_cvt_pk_bf16_f32 v109, v110, v111
	v_cvt_pk_bf16_f32 v110, v104, v105
	v_cvt_pk_bf16_f32 v111, v106, v107
	v_add_u32_e32 v173, 0x8000, v170
	global_store_dwordx4 v173, v[108:111], s[54:55]
	v_cvt_f32_ubyte0_e32 v128, v180
	v_cvt_f32_ubyte1_e32 v129, v180
	v_cvt_f32_ubyte2_e32 v130, v180
	v_cvt_f32_ubyte3_e32 v131, v180
	v_pk_mul_f32 v[128:129], v[128:129], s[14:15] op_sel_hi:[1,0]
	v_pk_mul_f32 v[130:131], v[130:131], s[14:15] op_sel_hi:[1,0]
	v_pk_fma_f32 v[100:101], v[100:101], v[128:129], v[154:155]
	v_pk_fma_f32 v[102:103], v[102:103], v[130:131], v[154:155]
	v_cvt_f32_ubyte0_e32 v128, v181
	v_cvt_f32_ubyte1_e32 v129, v181
	v_cvt_f32_ubyte2_e32 v130, v181
	v_cvt_f32_ubyte3_e32 v131, v181
	v_pk_mul_f32 v[128:129], v[128:129], s[14:15] op_sel_hi:[1,0]
	v_pk_mul_f32 v[130:131], v[130:131], s[14:15] op_sel_hi:[1,0]
	v_pk_fma_f32 v[96:97], v[96:97], v[128:129], v[154:155]
	v_pk_fma_f32 v[98:99], v[98:99], v[130:131], v[154:155]
	v_cvt_pk_bf16_f32 v100, v100, v101
	v_cvt_pk_bf16_f32 v101, v102, v103
	v_cvt_pk_bf16_f32 v102, v96, v97
	v_cvt_pk_bf16_f32 v103, v98, v99
	v_add_u32_e32 v173, 0x8000, v170
	global_store_dwordx4 v173, v[100:103], s[54:55] offset:256
	v_cvt_f32_ubyte0_e32 v128, v182
	v_cvt_f32_ubyte1_e32 v129, v182
	v_cvt_f32_ubyte2_e32 v130, v182
	v_cvt_f32_ubyte3_e32 v131, v182
	v_pk_mul_f32 v[128:129], v[128:129], s[14:15] op_sel_hi:[1,0]
	v_pk_mul_f32 v[130:131], v[130:131], s[14:15] op_sel_hi:[1,0]
	v_pk_fma_f32 v[92:93], v[92:93], v[128:129], v[154:155]
	v_pk_fma_f32 v[94:95], v[94:95], v[130:131], v[154:155]
	v_cvt_f32_ubyte0_e32 v128, v183
	v_cvt_f32_ubyte1_e32 v129, v183
	v_cvt_f32_ubyte2_e32 v130, v183
	v_cvt_f32_ubyte3_e32 v131, v183
	v_pk_mul_f32 v[128:129], v[128:129], s[14:15] op_sel_hi:[1,0]
	v_pk_mul_f32 v[130:131], v[130:131], s[14:15] op_sel_hi:[1,0]
	v_pk_fma_f32 v[88:89], v[88:89], v[128:129], v[154:155]
	v_pk_fma_f32 v[90:91], v[90:91], v[130:131], v[154:155]
	v_cvt_pk_bf16_f32 v92, v92, v93
	v_cvt_pk_bf16_f32 v93, v94, v95
	v_cvt_pk_bf16_f32 v94, v88, v89
	v_cvt_pk_bf16_f32 v95, v90, v91
	v_add_u32_e32 v173, 0x10000, v170
	global_store_dwordx4 v173, v[92:95], s[54:55]
	v_cvt_f32_ubyte0_e32 v128, v184
	v_cvt_f32_ubyte1_e32 v129, v184
	v_cvt_f32_ubyte2_e32 v130, v184
	v_cvt_f32_ubyte3_e32 v131, v184
	v_pk_mul_f32 v[128:129], v[128:129], s[14:15] op_sel_hi:[1,0]
	v_pk_mul_f32 v[130:131], v[130:131], s[14:15] op_sel_hi:[1,0]
	v_pk_fma_f32 v[84:85], v[84:85], v[128:129], v[154:155]
	v_pk_fma_f32 v[86:87], v[86:87], v[130:131], v[154:155]
	v_cvt_f32_ubyte0_e32 v128, v185
	v_cvt_f32_ubyte1_e32 v129, v185
	v_cvt_f32_ubyte2_e32 v130, v185
	v_cvt_f32_ubyte3_e32 v131, v185
	v_pk_mul_f32 v[128:129], v[128:129], s[14:15] op_sel_hi:[1,0]
	v_pk_mul_f32 v[130:131], v[130:131], s[14:15] op_sel_hi:[1,0]
	v_pk_fma_f32 v[80:81], v[80:81], v[128:129], v[154:155]
	v_pk_fma_f32 v[82:83], v[82:83], v[130:131], v[154:155]
	v_cvt_pk_bf16_f32 v84, v84, v85
	v_cvt_pk_bf16_f32 v85, v86, v87
	v_cvt_pk_bf16_f32 v86, v80, v81
	v_cvt_pk_bf16_f32 v87, v82, v83
	v_add_u32_e32 v173, 0x10000, v170
	global_store_dwordx4 v173, v[84:87], s[54:55] offset:256
	v_cvt_f32_ubyte0_e32 v128, v186
	v_cvt_f32_ubyte1_e32 v129, v186
	v_cvt_f32_ubyte2_e32 v130, v186
	v_cvt_f32_ubyte3_e32 v131, v186
	v_pk_mul_f32 v[128:129], v[128:129], s[14:15] op_sel_hi:[1,0]
	v_pk_mul_f32 v[130:131], v[130:131], s[14:15] op_sel_hi:[1,0]
	v_pk_fma_f32 v[76:77], v[76:77], v[128:129], v[154:155]
	v_pk_fma_f32 v[78:79], v[78:79], v[130:131], v[154:155]
	v_cvt_f32_ubyte0_e32 v128, v187
	v_cvt_f32_ubyte1_e32 v129, v187
	v_cvt_f32_ubyte2_e32 v130, v187
	v_cvt_f32_ubyte3_e32 v131, v187
	v_pk_mul_f32 v[128:129], v[128:129], s[14:15] op_sel_hi:[1,0]
	v_pk_mul_f32 v[130:131], v[130:131], s[14:15] op_sel_hi:[1,0]
	v_pk_fma_f32 v[72:73], v[72:73], v[128:129], v[154:155]
	v_pk_fma_f32 v[74:75], v[74:75], v[130:131], v[154:155]
	v_cvt_pk_bf16_f32 v76, v76, v77
	v_cvt_pk_bf16_f32 v77, v78, v79
	v_cvt_pk_bf16_f32 v78, v72, v73
	v_cvt_pk_bf16_f32 v79, v74, v75
	v_add_u32_e32 v173, 0x18000, v170
	global_store_dwordx4 v173, v[76:79], s[54:55]
	v_cvt_f32_ubyte0_e32 v128, v188
	v_cvt_f32_ubyte1_e32 v129, v188
	v_cvt_f32_ubyte2_e32 v130, v188
	v_cvt_f32_ubyte3_e32 v131, v188
	v_pk_mul_f32 v[128:129], v[128:129], s[14:15] op_sel_hi:[1,0]
	v_pk_mul_f32 v[130:131], v[130:131], s[14:15] op_sel_hi:[1,0]
	v_pk_fma_f32 v[68:69], v[68:69], v[128:129], v[154:155]
	v_pk_fma_f32 v[70:71], v[70:71], v[130:131], v[154:155]
	v_cvt_f32_ubyte0_e32 v128, v189
	v_cvt_f32_ubyte1_e32 v129, v189
	v_cvt_f32_ubyte2_e32 v130, v189
	v_cvt_f32_ubyte3_e32 v131, v189
	v_pk_mul_f32 v[128:129], v[128:129], s[14:15] op_sel_hi:[1,0]
	v_pk_mul_f32 v[130:131], v[130:131], s[14:15] op_sel_hi:[1,0]
	v_pk_fma_f32 v[64:65], v[64:65], v[128:129], v[154:155]
	v_pk_fma_f32 v[66:67], v[66:67], v[130:131], v[154:155]
	v_cvt_pk_bf16_f32 v68, v68, v69
	v_cvt_pk_bf16_f32 v69, v70, v71
	v_cvt_pk_bf16_f32 v70, v64, v65
	v_cvt_pk_bf16_f32 v71, v66, v67
	v_add_u32_e32 v173, 0x18000, v170
	global_store_dwordx4 v173, v[68:71], s[54:55] offset:256
	v_cvt_f32_ubyte0_e32 v128, v190
	v_cvt_f32_ubyte1_e32 v129, v190
	v_cvt_f32_ubyte2_e32 v130, v190
	v_cvt_f32_ubyte3_e32 v131, v190
	v_pk_mul_f32 v[128:129], v[128:129], s[14:15] op_sel_hi:[1,0]
	v_pk_mul_f32 v[130:131], v[130:131], s[14:15] op_sel_hi:[1,0]
	v_pk_fma_f32 v[60:61], v[60:61], v[128:129], v[154:155]
	v_pk_fma_f32 v[62:63], v[62:63], v[130:131], v[154:155]
	v_cvt_f32_ubyte0_e32 v128, v191
	v_cvt_f32_ubyte1_e32 v129, v191
	v_cvt_f32_ubyte2_e32 v130, v191
	v_cvt_f32_ubyte3_e32 v131, v191
	v_pk_mul_f32 v[128:129], v[128:129], s[14:15] op_sel_hi:[1,0]
	v_pk_mul_f32 v[130:131], v[130:131], s[14:15] op_sel_hi:[1,0]
	v_pk_fma_f32 v[56:57], v[56:57], v[128:129], v[154:155]
	v_pk_fma_f32 v[58:59], v[58:59], v[130:131], v[154:155]
	v_cvt_pk_bf16_f32 v60, v60, v61
	v_cvt_pk_bf16_f32 v61, v62, v63
	v_cvt_pk_bf16_f32 v62, v56, v57
	v_cvt_pk_bf16_f32 v63, v58, v59
	v_add_u32_e32 v173, 0x40000, v170
	global_store_dwordx4 v173, v[60:63], s[54:55]
	v_cvt_f32_ubyte0_e32 v128, v192
	v_cvt_f32_ubyte1_e32 v129, v192
	v_cvt_f32_ubyte2_e32 v130, v192
	v_cvt_f32_ubyte3_e32 v131, v192
	v_pk_mul_f32 v[128:129], v[128:129], s[14:15] op_sel_hi:[1,0]
	v_pk_mul_f32 v[130:131], v[130:131], s[14:15] op_sel_hi:[1,0]
	v_pk_fma_f32 v[52:53], v[52:53], v[128:129], v[154:155]
	v_pk_fma_f32 v[54:55], v[54:55], v[130:131], v[154:155]
	v_cvt_f32_ubyte0_e32 v128, v193
	v_cvt_f32_ubyte1_e32 v129, v193
	v_cvt_f32_ubyte2_e32 v130, v193
	v_cvt_f32_ubyte3_e32 v131, v193
	v_pk_mul_f32 v[128:129], v[128:129], s[14:15] op_sel_hi:[1,0]
	v_pk_mul_f32 v[130:131], v[130:131], s[14:15] op_sel_hi:[1,0]
	v_pk_fma_f32 v[48:49], v[48:49], v[128:129], v[154:155]
	v_pk_fma_f32 v[50:51], v[50:51], v[130:131], v[154:155]
	v_cvt_pk_bf16_f32 v52, v52, v53
	v_cvt_pk_bf16_f32 v53, v54, v55
	v_cvt_pk_bf16_f32 v54, v48, v49
	v_cvt_pk_bf16_f32 v55, v50, v51
	v_add_u32_e32 v173, 0x40000, v170
	global_store_dwordx4 v173, v[52:55], s[54:55] offset:256
	v_cvt_f32_ubyte0_e32 v128, v194
	v_cvt_f32_ubyte1_e32 v129, v194
	v_cvt_f32_ubyte2_e32 v130, v194
	v_cvt_f32_ubyte3_e32 v131, v194
	v_pk_mul_f32 v[128:129], v[128:129], s[14:15] op_sel_hi:[1,0]
	v_pk_mul_f32 v[130:131], v[130:131], s[14:15] op_sel_hi:[1,0]
	v_pk_fma_f32 v[44:45], v[44:45], v[128:129], v[154:155]
	v_pk_fma_f32 v[46:47], v[46:47], v[130:131], v[154:155]
	v_cvt_f32_ubyte0_e32 v128, v195
	v_cvt_f32_ubyte1_e32 v129, v195
	v_cvt_f32_ubyte2_e32 v130, v195
	v_cvt_f32_ubyte3_e32 v131, v195
	v_pk_mul_f32 v[128:129], v[128:129], s[14:15] op_sel_hi:[1,0]
	v_pk_mul_f32 v[130:131], v[130:131], s[14:15] op_sel_hi:[1,0]
	v_pk_fma_f32 v[40:41], v[40:41], v[128:129], v[154:155]
	v_pk_fma_f32 v[42:43], v[42:43], v[130:131], v[154:155]
	v_cvt_pk_bf16_f32 v44, v44, v45
	v_cvt_pk_bf16_f32 v45, v46, v47
	v_cvt_pk_bf16_f32 v46, v40, v41
	v_cvt_pk_bf16_f32 v47, v42, v43
	v_add_u32_e32 v173, 0x48000, v170
	global_store_dwordx4 v173, v[44:47], s[54:55]
	v_cvt_f32_ubyte0_e32 v128, v196
	v_cvt_f32_ubyte1_e32 v129, v196
	v_cvt_f32_ubyte2_e32 v130, v196
	v_cvt_f32_ubyte3_e32 v131, v196
	v_pk_mul_f32 v[128:129], v[128:129], s[14:15] op_sel_hi:[1,0]
	v_pk_mul_f32 v[130:131], v[130:131], s[14:15] op_sel_hi:[1,0]
	v_pk_fma_f32 v[36:37], v[36:37], v[128:129], v[154:155]
	v_pk_fma_f32 v[38:39], v[38:39], v[130:131], v[154:155]
	v_cvt_f32_ubyte0_e32 v128, v197
	v_cvt_f32_ubyte1_e32 v129, v197
	v_cvt_f32_ubyte2_e32 v130, v197
	v_cvt_f32_ubyte3_e32 v131, v197
	v_pk_mul_f32 v[128:129], v[128:129], s[14:15] op_sel_hi:[1,0]
	v_pk_mul_f32 v[130:131], v[130:131], s[14:15] op_sel_hi:[1,0]
	v_pk_fma_f32 v[32:33], v[32:33], v[128:129], v[154:155]
	v_pk_fma_f32 v[34:35], v[34:35], v[130:131], v[154:155]
	v_cvt_pk_bf16_f32 v36, v36, v37
	v_cvt_pk_bf16_f32 v37, v38, v39
	v_cvt_pk_bf16_f32 v38, v32, v33
	v_cvt_pk_bf16_f32 v39, v34, v35
	v_add_u32_e32 v173, 0x48000, v170
	global_store_dwordx4 v173, v[36:39], s[54:55] offset:256
	v_cvt_f32_ubyte0_e32 v128, v198
	v_cvt_f32_ubyte1_e32 v129, v198
	v_cvt_f32_ubyte2_e32 v130, v198
	v_cvt_f32_ubyte3_e32 v131, v198
	v_pk_mul_f32 v[128:129], v[128:129], s[14:15] op_sel_hi:[1,0]
	v_pk_mul_f32 v[130:131], v[130:131], s[14:15] op_sel_hi:[1,0]
	v_pk_fma_f32 v[28:29], v[28:29], v[128:129], v[154:155]
	v_pk_fma_f32 v[30:31], v[30:31], v[130:131], v[154:155]
	v_cvt_f32_ubyte0_e32 v128, v199
	v_cvt_f32_ubyte1_e32 v129, v199
	v_cvt_f32_ubyte2_e32 v130, v199
	v_cvt_f32_ubyte3_e32 v131, v199
	v_pk_mul_f32 v[128:129], v[128:129], s[14:15] op_sel_hi:[1,0]
	v_pk_mul_f32 v[130:131], v[130:131], s[14:15] op_sel_hi:[1,0]
	v_pk_fma_f32 v[24:25], v[24:25], v[128:129], v[154:155]
	v_pk_fma_f32 v[26:27], v[26:27], v[130:131], v[154:155]
	v_cvt_pk_bf16_f32 v28, v28, v29
	v_cvt_pk_bf16_f32 v29, v30, v31
	v_cvt_pk_bf16_f32 v30, v24, v25
	v_cvt_pk_bf16_f32 v31, v26, v27
	v_add_u32_e32 v173, 0x50000, v170
	global_store_dwordx4 v173, v[28:31], s[54:55]
	v_cvt_f32_ubyte0_e32 v128, v200
	v_cvt_f32_ubyte1_e32 v129, v200
	v_cvt_f32_ubyte2_e32 v130, v200
	v_cvt_f32_ubyte3_e32 v131, v200
	v_pk_mul_f32 v[128:129], v[128:129], s[14:15] op_sel_hi:[1,0]
	v_pk_mul_f32 v[130:131], v[130:131], s[14:15] op_sel_hi:[1,0]
	v_pk_fma_f32 v[20:21], v[20:21], v[128:129], v[154:155]
	v_pk_fma_f32 v[22:23], v[22:23], v[130:131], v[154:155]
	v_cvt_f32_ubyte0_e32 v128, v201
	v_cvt_f32_ubyte1_e32 v129, v201
	v_cvt_f32_ubyte2_e32 v130, v201
	v_cvt_f32_ubyte3_e32 v131, v201
	v_pk_mul_f32 v[128:129], v[128:129], s[14:15] op_sel_hi:[1,0]
	v_pk_mul_f32 v[130:131], v[130:131], s[14:15] op_sel_hi:[1,0]
	v_pk_fma_f32 v[16:17], v[16:17], v[128:129], v[154:155]
	v_pk_fma_f32 v[18:19], v[18:19], v[130:131], v[154:155]
	v_cvt_pk_bf16_f32 v20, v20, v21
	v_cvt_pk_bf16_f32 v21, v22, v23
	v_cvt_pk_bf16_f32 v22, v16, v17
	v_cvt_pk_bf16_f32 v23, v18, v19
	v_add_u32_e32 v173, 0x50000, v170
	global_store_dwordx4 v173, v[20:23], s[54:55] offset:256
	v_cvt_f32_ubyte0_e32 v128, v202
	v_cvt_f32_ubyte1_e32 v129, v202
	v_cvt_f32_ubyte2_e32 v130, v202
	v_cvt_f32_ubyte3_e32 v131, v202
	v_pk_mul_f32 v[128:129], v[128:129], s[14:15] op_sel_hi:[1,0]
	v_pk_mul_f32 v[130:131], v[130:131], s[14:15] op_sel_hi:[1,0]
	v_pk_fma_f32 v[12:13], v[12:13], v[128:129], v[154:155]
	v_pk_fma_f32 v[14:15], v[14:15], v[130:131], v[154:155]
	v_cvt_f32_ubyte0_e32 v128, v203
	v_cvt_f32_ubyte1_e32 v129, v203
	v_cvt_f32_ubyte2_e32 v130, v203
	v_cvt_f32_ubyte3_e32 v131, v203
	v_pk_mul_f32 v[128:129], v[128:129], s[14:15] op_sel_hi:[1,0]
	v_pk_mul_f32 v[130:131], v[130:131], s[14:15] op_sel_hi:[1,0]
	v_pk_fma_f32 v[8:9], v[8:9], v[128:129], v[154:155]
	v_pk_fma_f32 v[10:11], v[10:11], v[130:131], v[154:155]
	v_cvt_pk_bf16_f32 v12, v12, v13
	v_cvt_pk_bf16_f32 v13, v14, v15
	v_cvt_pk_bf16_f32 v14, v8, v9
	v_cvt_pk_bf16_f32 v15, v10, v11
	v_add_u32_e32 v173, 0x58000, v170
	global_store_dwordx4 v173, v[12:15], s[54:55]
	v_cvt_f32_ubyte0_e32 v128, v204
	v_cvt_f32_ubyte1_e32 v129, v204
	v_cvt_f32_ubyte2_e32 v130, v204
	v_cvt_f32_ubyte3_e32 v131, v204
	v_pk_mul_f32 v[128:129], v[128:129], s[14:15] op_sel_hi:[1,0]
	v_pk_mul_f32 v[130:131], v[130:131], s[14:15] op_sel_hi:[1,0]
	v_pk_fma_f32 v[4:5], v[4:5], v[128:129], v[154:155]
	v_pk_fma_f32 v[6:7], v[6:7], v[130:131], v[154:155]
	v_cvt_f32_ubyte0_e32 v128, v205
	v_cvt_f32_ubyte1_e32 v129, v205
	v_cvt_f32_ubyte2_e32 v130, v205
	v_cvt_f32_ubyte3_e32 v131, v205
	v_pk_mul_f32 v[128:129], v[128:129], s[14:15] op_sel_hi:[1,0]
	v_pk_mul_f32 v[130:131], v[130:131], s[14:15] op_sel_hi:[1,0]
	v_pk_fma_f32 v[0:1], v[0:1], v[128:129], v[154:155]
	v_pk_fma_f32 v[2:3], v[2:3], v[130:131], v[154:155]
	v_cvt_pk_bf16_f32 v4, v4, v5
	v_cvt_pk_bf16_f32 v5, v6, v7
	v_cvt_pk_bf16_f32 v6, v0, v1
	v_cvt_pk_bf16_f32 v7, v2, v3
	v_add_u32_e32 v173, 0x58000, v170
	global_store_dwordx4 v173, v[4:7], s[54:55] offset:256
.Lbra_end:
	s_and_b64 vcc, exec, s[2:3]
	s_mov_b64 s[2:3], -1
	s_cbranch_vccnz .LBB0_788
	s_andn2_b64 vcc, exec, s[0:1]
	s_cbranch_vccnz .LBB0_787
	s_barrier
	s_branch .LBB0_787

.LBB0_1588:
	v_lshrrev_b32_e32 v0, 6, v168
	v_lshl_add_u32 v0, s12, 3, v0
	s_mov_b32 s0, 0x8800
	v_cmp_gt_i32_e32 vcc, s0, v0
	s_and_saveexec_b64 s[0:1], vcc
	s_cbranch_execz .LBB0_1609
	v_mbcnt_lo_u32_b32 v2, -1, 0
	v_mbcnt_hi_u32_b32 v2, -1, v2
	v_and_b32_e32 v4, 64, v2
	v_add_u32_e32 v4, 64, v4
	v_xor_b32_e32 v5, 1, v2
	v_cmp_lt_i32_e32 vcc, v5, v4
	v_and_b32_e32 v20, 7, v168
	v_and_b32_e32 v1, 63, v168
	v_cndmask_b32_e32 v5, v2, v5, vcc
	v_lshlrev_b32_e32 v38, 2, v5
	v_xor_b32_e32 v5, 2, v2
	v_cmp_lt_i32_e32 vcc, v5, v4
	v_lshlrev_b32_e32 v14, 2, v1
	v_and_b32_e32 v26, 12, v14
	v_cndmask_b32_e32 v5, v2, v5, vcc
	v_lshlrev_b32_e32 v39, 2, v5
	v_xor_b32_e32 v5, 4, v2
	v_cmp_lt_i32_e32 vcc, v5, v4
	v_readlane_b32 s16, v244, 1
	v_mov_b32_e32 v3, 0
	v_cndmask_b32_e32 v5, v2, v5, vcc
	v_lshlrev_b32_e32 v40, 2, v5
	v_xor_b32_e32 v5, 8, v2
	v_cmp_lt_i32_e32 vcc, v5, v4
	v_readlane_b32 s18, v244, 3
	v_readlane_b32 s19, v244, 4
	v_cndmask_b32_e32 v5, v2, v5, vcc
	v_lshlrev_b32_e32 v41, 2, v5
	v_xor_b32_e32 v5, 16, v2
	v_cmp_lt_i32_e32 vcc, v5, v4
	v_readlane_b32 s22, v244, 7
	v_readlane_b32 s23, v244, 8
	v_cndmask_b32_e32 v5, v2, v5, vcc
	v_lshlrev_b32_e32 v42, 2, v5
	v_xor_b32_e32 v5, 32, v2
	v_cmp_lt_i32_e32 vcc, v5, v4
	v_lshlrev_b32_e32 v4, 3, v168
	v_and_b32_e32 v22, 0x1c0, v4
	v_cndmask_b32_e32 v2, v2, v5, vcc
	v_lshlrev_b32_e32 v43, 2, v2
	v_lshlrev_b32_e32 v2, 1, v168
	v_and_b32_e32 v18, 16, v2
	v_cvt_f32_ubyte0_e32 v2, v20
	v_mul_f32_e32 v2, 0xbfd49a78, v2
	v_exp_f32_e32 v44, v2
	v_bfe_u32 v2, v168, 2, 1
	v_lshlrev_b32_e32 v24, 5, v2
	v_cmp_eq_u32_e64 s[4:5], 0, v2
	v_cvt_f32_ubyte0_e32 v2, v26
	v_mul_f32_e32 v2, 0xbf549a78, v2
	v_exp_f32_e32 v45, v2
	v_or_b32_e32 v2, 1, v26
	v_cvt_f32_ubyte0_e32 v2, v2
	v_mul_f32_e32 v2, 0xbf549a78, v2
	v_exp_f32_e32 v46, v2
	v_or_b32_e32 v2, 2, v26
	v_cvt_f32_ubyte0_e32 v2, v2
	v_mul_f32_e32 v2, 0xbf549a78, v2
	v_exp_f32_e32 v47, v2
	v_or_b32_e32 v2, 3, v26
	v_cvt_f32_ubyte0_e32 v2, v2
	v_mul_f32_e32 v2, 0xbf549a78, v2
	v_exp_f32_e32 v48, v2
	v_lshlrev_b32_e32 v2, 4, v1
	v_or_b32_e32 v8, v24, v26
	v_lshl_add_u64 v[4:5], s[18:19], 0, v[2:3]
	v_lshlrev_b32_e32 v2, 3, v1
	v_lshlrev_b32_e32 v16, 1, v1
	v_readlane_b32 s17, v244, 2
	v_readlane_b32 s20, v244, 5
	v_readlane_b32 s21, v244, 6
	v_readlane_b32 s24, v244, 9
	v_readlane_b32 s25, v244, 10
	v_readlane_b32 s26, v244, 11
	v_readlane_b32 s27, v244, 12
	v_readlane_b32 s28, v244, 13
	v_readlane_b32 s29, v244, 14
	v_lshl_add_u64 v[6:7], s[22:23], 0, v[2:3]
	v_lshlrev_b32_e32 v2, 2, v8
	s_lshl_b32 s13, s70, 3
	v_cmp_gt_u32_e32 vcc, 16, v1
	v_cmp_gt_u32_e64 s[2:3], 8, v1
	v_lshl_add_u64 v[8:9], s[26:27], 0, v[2:3]
	v_lshl_add_u64 v[10:11], s[28:29], 0, v[2:3]
	s_mov_b64 s[16:17], 0
	s_mov_b32 s19, 0x78787879
	s_movk_i32 s20, 0xff
	s_movk_i32 s21, 0x300
	v_mov_b64_e32 v[12:13], s[60:61]
	v_lshlrev_b32_e32 v14, 1, v14
	v_mov_b32_e32 v15, v3
	s_mov_b32 s22, 0xffff0000
	v_mov_b32_e32 v49, 0x358637bd
	s_mov_b32 s23, 0x800000
	s_movk_i32 s24, 0x7fff
	v_lshlrev_b32_e32 v16, 1, v16
	v_lshlrev_b32_e32 v18, 1, v18
	v_lshlrev_b32_e32 v20, 1, v20
	v_lshlrev_b32_e32 v2, 1, v22
	v_lshlrev_b32_e32 v22, 1, v24
	v_lshlrev_b32_e32 v24, 1, v26
	s_mov_b32 s18, 0x3e38aa3b
	s_mov_b32 s25, 0x87ff
	v_mov_b32_e32 v50, 1
	v_mov_b32_e32 v17, v3
	v_readlane_b32 s30, v244, 15
	v_readlane_b32 s31, v244, 16
	global_load_dwordx4 v[70:73], v[4:5], off offset:1024
	global_load_dwordx2 v[74:75], v[6:7], off offset:512
	global_load_dwordx4 v[76:79], v[8:9], off offset:256
	global_load_dwordx4 v[102:105], v[8:9], off offset:320
	global_load_dwordx4 v[106:109], v[10:11], off offset:256
	global_load_dwordx4 v[110:113], v[10:11], off offset:320
	v_add_u32_e32 v80, v18, v20
	v_mov_b32_e32 v81, 0
	v_add3_u32 v82, v2, v22, v24
	v_mov_b32_e32 v83, 0
	v_mov_b32_e32 v163, 0
	v_ashrrev_i32_e32 v1, 31, v0
	v_lshlrev_b64 v[164:165], 12, v[0:1]
	v_lshl_add_u64 v[164:165], s[58:59], 0, v[164:165]
	v_lshl_add_u64 v[28:29], v[164:165], 0, v[14:15]
	v_lshl_add_u64 v[54:55], v[164:165], 0, v[16:17]
	v_lshl_add_u64 v[84:85], v[164:165], 0, v[82:83]
	v_lshl_add_u64 v[114:115], v[164:165], 0, v[80:81]
	global_load_dwordx2 v[120:121], v[28:29], off
	global_load_dword v118, v[54:55], off offset:512
	global_load_dwordx2 v[86:87], v[84:85], off offset:832
	global_load_dwordx2 v[88:89], v[84:85], off offset:864
	global_load_dwordx2 v[90:91], v[84:85], off offset:2368
	global_load_dwordx2 v[92:93], v[84:85], off offset:2400
	s_and_saveexec_b64 s[8:9], vcc
	global_load_dwordx2 v[94:95], v[84:85], off offset:1856
	global_load_dwordx2 v[96:97], v[84:85], off offset:1888
	global_load_dwordx2 v[98:99], v[84:85], off offset:3392
	global_load_dwordx2 v[100:101], v[84:85], off offset:3424
	global_load_ushort v116, v[114:115], off offset:768
	global_load_ushort v117, v[114:115], off offset:784
	s_or_b64 exec, exec, s[8:9]
	s_branch .LBB0_1591

.LBB0_1591:
	s_waitcnt vmcnt(0)
	v_mov_b64_e32 v[32:33], v[120:121]
	v_mov_b64_e32 v[142:143], v[86:87]
	v_mov_b64_e32 v[144:145], v[88:89]
	v_mov_b64_e32 v[146:147], v[90:91]
	v_mov_b64_e32 v[148:149], v[92:93]
	v_mov_b64_e32 v[150:151], v[94:95]
	v_mov_b64_e32 v[152:153], v[96:97]
	v_mov_b64_e32 v[154:155], v[98:99]
	v_mov_b64_e32 v[156:157], v[100:101]
	v_mov_b32_e32 v158, v116
	v_mov_b32_e32 v159, v117
	v_mov_b32_e32 v160, v118
	v_ashrrev_i32_e32 v1, 31, v0
	v_lshlrev_b64 v[26:27], 12, v[0:1]
	v_lshl_add_u64 v[26:27], s[58:59], 0, v[26:27]
	v_add_u32_e32 v162, s13, v0
	v_min_i32_e32 v162, 0x87ff, v162
	v_lshlrev_b64 v[164:165], 12, v[162:163]
	v_lshl_add_u64 v[164:165], s[58:59], 0, v[164:165]
	v_lshl_add_u64 v[28:29], v[164:165], 0, v[14:15]
	v_lshl_add_u64 v[54:55], v[164:165], 0, v[16:17]
	v_lshl_add_u64 v[84:85], v[164:165], 0, v[82:83]
	v_lshl_add_u64 v[114:115], v[164:165], 0, v[80:81]
	global_load_dwordx2 v[120:121], v[28:29], off
	global_load_dword v118, v[54:55], off offset:512
	global_load_dwordx2 v[86:87], v[84:85], off offset:832
	global_load_dwordx2 v[88:89], v[84:85], off offset:864
	global_load_dwordx2 v[90:91], v[84:85], off offset:2368
	global_load_dwordx2 v[92:93], v[84:85], off offset:2400
	s_and_saveexec_b64 s[8:9], vcc
	global_load_dwordx2 v[94:95], v[84:85], off offset:1856
	global_load_dwordx2 v[96:97], v[84:85], off offset:1888
	global_load_dwordx2 v[98:99], v[84:85], off offset:3392
	global_load_dwordx2 v[100:101], v[84:85], off offset:3424
	global_load_ushort v116, v[114:115], off offset:768
	global_load_ushort v117, v[114:115], off offset:784
	s_or_b64 exec, exec, s[8:9]
	v_mov_b64_e32 v[28:29], v[70:71]
	v_mov_b64_e32 v[30:31], v[72:73]
	v_lshlrev_b32_e32 v34, 16, v32
	v_and_b32_e32 v32, 0xffff0000, v32
	v_lshlrev_b32_e32 v35, 16, v33
	v_and_b32_e32 v33, 0xffff0000, v33
	v_mov_b32_e32 v36, v34
	v_mov_b32_e32 v37, v32
	v_mov_b32_e32 v52, v33
	v_mov_b32_e32 v53, v35
	v_pk_mul_f32 v[36:37], v[36:37], v[36:37]
	v_pk_mul_f32 v[52:53], v[52:53], v[52:53]
	v_add_f32_e32 v1, v36, v37
	v_add_f32_e32 v1, v53, v1
	v_add_f32_e32 v1, v52, v1
	ds_bpermute_b32 v19, v38, v1
	v_mad_i64_i32 v[36:37], s[6:7], v0, s21, v[12:13]
	v_mov_b32_e32 v56, v28
	v_mov_b32_e32 v57, v30
	s_waitcnt lgkmcnt(0)
	v_add_f32_e32 v1, v1, v19
	ds_bpermute_b32 v19, v39, v1
	v_mov_b32_e32 v30, v29
	v_lshl_add_u64 v[52:53], v[36:37], 0, v[14:15]
	s_waitcnt lgkmcnt(0)
	v_add_f32_e32 v1, v1, v19
	ds_bpermute_b32 v19, v40, v1
	s_waitcnt lgkmcnt(0)
	v_add_f32_e32 v1, v1, v19
	ds_bpermute_b32 v19, v41, v1
	s_waitcnt lgkmcnt(0)
	v_add_f32_e32 v1, v1, v19
	ds_bpermute_b32 v19, v42, v1
	s_waitcnt lgkmcnt(0)
	v_add_f32_e32 v1, v1, v19
	ds_bpermute_b32 v19, v43, v1
	s_waitcnt lgkmcnt(0)
	v_add_f32_e32 v1, v1, v19
	v_fmamk_f32 v1, v1, 0x3b800000, v49
	v_mul_f32_e32 v19, 0x4b800000, v1
	v_cmp_gt_f32_e64 s[6:7], s23, v1
	s_nop 1
	v_cndmask_b32_e64 v1, v1, v19, s[6:7]
	v_rsq_f32_e32 v1, v1
	s_nop 0
	v_mul_f32_e32 v19, 0x45800000, v1
	v_cndmask_b32_e64 v28, v1, v19, s[6:7]
	v_pk_mul_f32 v[34:35], v[28:29], v[34:35] op_sel_hi:[0,1]
	v_pk_mul_f32 v[28:29], v[28:29], v[32:33] op_sel_hi:[0,1]
	v_pk_mul_f32 v[28:29], v[30:31], v[28:29]
	v_pk_mul_f32 v[32:33], v[56:57], v[34:35]
	v_and_b32_sdwa v21, v29, v50 dst_sel:DWORD dst_unused:UNUSED_PAD src0_sel:WORD_1 src1_sel:DWORD
	v_and_b32_sdwa v23, v28, v50 dst_sel:DWORD dst_unused:UNUSED_PAD src0_sel:WORD_1 src1_sel:DWORD
	v_and_b32_sdwa v1, v33, v50 dst_sel:DWORD dst_unused:UNUSED_PAD src0_sel:WORD_1 src1_sel:DWORD
	v_and_b32_sdwa v19, v32, v50 dst_sel:DWORD dst_unused:UNUSED_PAD src0_sel:WORD_1 src1_sel:DWORD
	v_add3_u32 v21, v29, v21, s24
	v_add3_u32 v23, v28, v23, s24
	v_add3_u32 v19, v32, v19, s24
	v_add3_u32 v1, v33, v1, s24
	v_and_b32_e32 v21, 0xffff0000, v21
	v_and_b32_e32 v23, 0xffff0000, v23
	v_or_b32_sdwa v29, v21, v1 dst_sel:DWORD dst_unused:UNUSED_PAD src0_sel:DWORD src1_sel:WORD_1
	v_or_b32_sdwa v28, v23, v19 dst_sel:DWORD dst_unused:UNUSED_PAD src0_sel:DWORD src1_sel:WORD_1
	global_store_dwordx2 v[52:53], v[28:29], off
	v_mov_b32_e32 v1, v160
	s_nop 0
	v_mov_b64_e32 v[28:29], v[74:75]
	v_mul_hi_i32 v21, v0, s19
	v_lshrrev_b32_e32 v23, 31, v21
	v_ashrrev_i32_e32 v21, 11, v21
	v_add_u32_e32 v21, v21, v23
	v_mul_i32_i24_e32 v21, 0x1100, v21
	v_sub_u32_e32 v21, v0, v21
	v_cmp_lt_i32_e64 s[6:7], s20, v21
	v_add_u32_e32 v23, 0xffffff00, v21
	v_and_b32_e32 v21, 63, v21
	v_ashrrev_i32_e32 v23, 6, v23
	v_cvt_f32_i32_e32 v34, v23
	s_and_b64 s[26:27], s[6:7], vcc
	s_nop 0
	v_lshlrev_b32_e32 v30, 16, v1
	v_and_b32_e32 v31, 0xffff0000, v1
	v_pk_mul_f32 v[32:33], v[30:31], v[30:31]
	s_nop 0
	v_add_f32_e32 v1, v32, v33
	ds_bpermute_b32 v19, v38, v1
	v_lshl_add_u64 v[32:33], v[36:37], 0, v[16:17]
	s_waitcnt lgkmcnt(0)
	v_add_f32_e32 v1, v1, v19
	ds_bpermute_b32 v19, v39, v1
	s_waitcnt lgkmcnt(0)
	v_add_f32_e32 v1, v1, v19
	ds_bpermute_b32 v19, v40, v1
	s_waitcnt lgkmcnt(0)
	v_add_f32_e32 v1, v1, v19
	ds_bpermute_b32 v19, v41, v1
	s_waitcnt lgkmcnt(0)
	v_add_f32_e32 v1, v1, v19
	ds_bpermute_b32 v19, v42, v1
	s_waitcnt lgkmcnt(0)
	v_add_f32_e32 v1, v1, v19
	ds_bpermute_b32 v19, v43, v1
	s_waitcnt lgkmcnt(0)
	v_add_f32_e32 v1, v1, v19
	v_fmamk_f32 v1, v1, 0x3c000000, v49
	v_mul_f32_e32 v19, 0x4b800000, v1
	v_cmp_gt_f32_e64 s[8:9], s23, v1
	s_nop 1
	v_cndmask_b32_e64 v1, v1, v19, s[8:9]
	v_rsq_f32_e32 v19, v1
	v_cvt_f32_ubyte0_e32 v1, v21
	v_mul_f32_e32 v21, 0x45800000, v19
	v_cndmask_b32_e64 v36, v19, v21, s[8:9]
	v_pk_mul_f32 v[30:31], v[36:37], v[30:31] op_sel_hi:[0,1]
	s_nop 0
	v_pk_mul_f32 v[28:29], v[28:29], v[30:31]
	s_nop 0
	v_and_b32_sdwa v21, v28, v50 dst_sel:DWORD dst_unused:UNUSED_PAD src0_sel:WORD_1 src1_sel:DWORD
	v_and_b32_sdwa v19, v29, v50 dst_sel:DWORD dst_unused:UNUSED_PAD src0_sel:WORD_1 src1_sel:DWORD
	v_add3_u32 v21, v28, v21, s24
	v_add3_u32 v19, v29, v19, s24
	v_lshrrev_b32_e32 v21, 16, v21
	v_and_or_b32 v19, v19, s22, v21
	global_store_dword v[32:33], v19, off offset:512
	s_and_saveexec_b64 s[8:9], s[26:27]
	s_cbranch_execz .LBB0_1593
	v_mov_b32_e32 v19, v3
	v_lshl_add_u64 v[28:29], v[26:27], 0, v[18:19]
	v_mov_b32_e32 v21, v3
	v_lshl_add_u64 v[28:29], v[28:29], 0, v[20:21]
	v_mov_b32_e32 v19, v158
	v_mov_b32_e32 v21, v159
	v_cndmask_b32_e64 v23, v1, v34, s[2:3]
	v_mul_f32_e32 v23, v44, v23
	v_mul_f32_e32 v23, 0.15915494, v23
	v_sin_f32_e32 v25, v23
	v_cos_f32_e32 v23, v23
	s_nop 0
	v_lshlrev_b32_e32 v19, 16, v19
	s_nop 0
	v_lshlrev_b32_e32 v21, 16, v21
	v_mul_f32_e32 v30, v25, v21
	v_mul_f32_e32 v21, v23, v21
	v_fma_f32 v23, v23, v19, -v30
	v_fmac_f32_e32 v21, v25, v19
	v_bfe_u32 v19, v23, 16, 1
	v_bfe_u32 v25, v21, 16, 1
	v_add3_u32 v19, v23, v19, s24
	v_add3_u32 v21, v21, v25, s24
	global_store_short_d16_hi v[28:29], v19, off offset:768
	global_store_short_d16_hi v[28:29], v21, off offset:784
.LBB0_1593:
	s_or_b64 exec, exec, s[8:9]
	v_lshl_add_u64 v[26:27], v[26:27], 0, v[2:3]
	v_mov_b32_e32 v23, v3
	v_lshl_add_u64 v[26:27], v[26:27], 0, v[22:23]
	v_mov_b32_e32 v25, v3
	v_lshl_add_u64 v[26:27], v[26:27], 0, v[24:25]
	v_mov_b64_e32 v[28:29], v[142:143]
	v_mov_b64_e32 v[36:37], v[144:145]
	v_mov_b64_e32 v[30:31], v[76:77]
	v_mov_b64_e32 v[32:33], v[78:79]
	v_mov_b64_e32 v[52:53], v[102:103]
	v_mov_b64_e32 v[54:55], v[104:105]
	v_cndmask_b32_e64 v1, v1, v34, s[4:5]
	s_nop 0
	v_and_b32_e32 v56, 0xffff0000, v29
	v_lshlrev_b32_e32 v57, 16, v29
	v_lshlrev_b32_e32 v60, 16, v28
	v_and_b32_e32 v61, 0xffff0000, v28
	s_nop 0
	v_lshlrev_b32_e32 v28, 16, v36
	v_and_b32_e32 v29, 0xffff0000, v36
	v_and_b32_e32 v58, 0xffff0000, v37
	v_lshlrev_b32_e32 v59, 16, v37
	v_pk_mul_f32 v[62:63], v[28:29], v[28:29]
	v_pk_mul_f32 v[36:37], v[58:59], v[58:59]
	v_pk_fma_f32 v[62:63], v[60:61], v[60:61], v[62:63]
	v_pk_fma_f32 v[36:37], v[56:57], v[56:57], v[36:37]
	v_add_f32_e32 v19, v62, v63
	v_add_f32_e32 v19, v37, v19
	v_add_f32_e32 v19, v36, v19
	ds_bpermute_b32 v21, v38, v19
	s_waitcnt lgkmcnt(0)
	v_add_f32_e32 v19, v19, v21
	ds_bpermute_b32 v21, v39, v19
	s_waitcnt lgkmcnt(0)
	v_add_f32_e32 v19, v19, v21
	ds_bpermute_b32 v21, v40, v19
	s_waitcnt lgkmcnt(0)
	v_add_f32_e32 v19, v19, v21
	v_fmamk_f32 v19, v19, 0x3c800000, v49
	v_mul_f32_e32 v21, 0x4b800000, v19
	v_cmp_gt_f32_e64 s[8:9], s23, v19
	s_nop 1
	v_cndmask_b32_e64 v19, v19, v21, s[8:9]
	v_rsq_f32_e32 v19, v19
	s_nop 0
	v_mul_f32_e32 v21, 0x45800000, v19
	v_cndmask_b32_e64 v36, v19, v21, s[8:9]
	s_nop 0
	v_mul_f32_e32 v19, v32, v36
	v_pk_mul_f32 v[30:31], v[30:31], v[36:37] op_sel_hi:[1,0]
	s_nop 0
	v_pk_mul_f32 v[52:53], v[52:53], v[36:37] op_sel_hi:[1,0]
	v_mul_f32_e32 v21, v54, v36
	v_mov_b32_e32 v32, v55
	v_mul_f32_e32 v37, v19, v57
	v_mul_f32_e32 v35, v21, v59
	v_pk_mul_f32 v[32:33], v[32:33], v[36:37] op_sel_hi:[1,0]
	v_mov_b32_e32 v59, v56
	v_pk_mul_f32 v[30:31], v[30:31], v[60:61]
	v_pk_mul_f32 v[28:29], v[52:53], v[28:29]
	v_pk_mul_f32 v[32:33], v[32:33], v[58:59]
	s_and_saveexec_b64 s[8:9], s[6:7]
	s_cbranch_execz .LBB0_1595
	v_mul_f32_e32 v19, v45, v1
	v_mul_f32_e32 v19, 0.15915494, v19
	v_cos_f32_e32 v52, v19
	v_sin_f32_e32 v54, v19
	v_mul_f32_e32 v19, v46, v1
	v_mul_f32_e32 v19, 0.15915494, v19
	v_mul_f32_e32 v23, v48, v1
	v_cos_f32_e32 v53, v19
	v_sin_f32_e32 v55, v19
	v_mul_f32_e32 v19, v47, v1
	v_mul_f32_e32 v23, 0.15915494, v23
	v_mul_f32_e32 v19, 0.15915494, v19
	v_cos_f32_e32 v59, v23
	v_sin_f32_e32 v58, v23
	v_cos_f32_e32 v21, v19
	v_sin_f32_e32 v19, v19
	v_pk_mul_f32 v[56:57], v[54:55], v[28:29]
	v_pk_mul_f32 v[64:65], v[58:59], v[32:33]
	v_mul_f32_e32 v34, v21, v37
	v_mul_f32_e32 v36, v19, v35
	v_mul_f32_e32 v60, v21, v35
	v_mul_f32_e32 v62, v19, v37
	v_mov_b32_e32 v35, v65
	v_mov_b32_e32 v37, v64
	v_mov_b32_e32 v64, v59
	v_mov_b32_e32 v65, v58
	v_pk_mul_f32 v[32:33], v[64:65], v[32:33]
	v_pk_mul_f32 v[54:55], v[54:55], v[30:31]
	v_mov_b32_e32 v61, v32
	v_mov_b32_e32 v63, v33
	v_pk_fma_f32 v[30:31], v[52:53], v[30:31], v[56:57] neg_lo:[0,0,1] neg_hi:[0,0,1]
	v_pk_add_f32 v[56:57], v[34:35], v[36:37] neg_lo:[0,1] neg_hi:[0,1]
	v_pk_add_f32 v[32:33], v[60:61], v[62:63]
	v_pk_fma_f32 v[28:29], v[52:53], v[28:29], v[54:55]
	v_mov_b32_e32 v35, v32
	v_mov_b32_e32 v32, v33
	v_mov_b32_e32 v37, v56
	v_mov_b32_e32 v33, v57
.LBB0_1595:
	s_or_b64 exec, exec, s[8:9]
	v_mov_b32_e32 v36, v30
	v_mov_b32_e32 v30, v31
	v_mov_b32_e32 v31, v33
	v_pk_mul_f32 v[30:31], v[30:31], s[18:19] op_sel_hi:[1,0]
	v_pk_mul_f32 v[36:37], v[36:37], s[18:19] op_sel_hi:[1,0]
	v_and_b32_sdwa v23, v31, v50 dst_sel:DWORD dst_unused:UNUSED_PAD src0_sel:WORD_1 src1_sel:DWORD
	v_and_b32_sdwa v25, v30, v50 dst_sel:DWORD dst_unused:UNUSED_PAD src0_sel:WORD_1 src1_sel:DWORD
	v_and_b32_sdwa v19, v37, v50 dst_sel:DWORD dst_unused:UNUSED_PAD src0_sel:WORD_1 src1_sel:DWORD
	v_and_b32_sdwa v21, v36, v50 dst_sel:DWORD dst_unused:UNUSED_PAD src0_sel:WORD_1 src1_sel:DWORD
	v_add3_u32 v23, v31, v23, s24
	v_add3_u32 v25, v30, v25, s24
	v_mov_b32_e32 v34, v28
	v_mov_b32_e32 v28, v29
	v_mov_b32_e32 v29, v32
	v_add3_u32 v21, v36, v21, s24
	v_add3_u32 v19, v37, v19, s24
	v_and_b32_e32 v23, 0xffff0000, v23
	v_and_b32_e32 v25, 0xffff0000, v25
	v_pk_mul_f32 v[28:29], v[28:29], s[18:19] op_sel_hi:[1,0]
	v_or_b32_sdwa v31, v23, v19 dst_sel:DWORD dst_unused:UNUSED_PAD src0_sel:DWORD src1_sel:WORD_1
	v_or_b32_sdwa v30, v25, v21 dst_sel:DWORD dst_unused:UNUSED_PAD src0_sel:DWORD src1_sel:WORD_1
	v_pk_mul_f32 v[34:35], v[34:35], s[18:19] op_sel_hi:[1,0]
	v_and_b32_sdwa v23, v29, v50 dst_sel:DWORD dst_unused:UNUSED_PAD src0_sel:WORD_1 src1_sel:DWORD
	v_and_b32_sdwa v25, v28, v50 dst_sel:DWORD dst_unused:UNUSED_PAD src0_sel:WORD_1 src1_sel:DWORD
	v_and_b32_sdwa v19, v35, v50 dst_sel:DWORD dst_unused:UNUSED_PAD src0_sel:WORD_1 src1_sel:DWORD
	v_and_b32_sdwa v21, v34, v50 dst_sel:DWORD dst_unused:UNUSED_PAD src0_sel:WORD_1 src1_sel:DWORD
	v_add3_u32 v23, v29, v23, s24
	v_add3_u32 v25, v28, v25, s24
	v_add3_u32 v21, v34, v21, s24
	v_add3_u32 v19, v35, v19, s24
	v_and_b32_e32 v23, 0xffff0000, v23
	v_and_b32_e32 v25, 0xffff0000, v25
	v_or_b32_sdwa v29, v23, v19 dst_sel:DWORD dst_unused:UNUSED_PAD src0_sel:DWORD src1_sel:WORD_1
	v_or_b32_sdwa v28, v25, v21 dst_sel:DWORD dst_unused:UNUSED_PAD src0_sel:DWORD src1_sel:WORD_1
	global_store_dwordx2 v[26:27], v[30:31], off offset:832
	global_store_dwordx2 v[26:27], v[28:29], off offset:864
	v_mov_b32_e32 v28, 0
	v_mov_b32_e32 v29, 0
	v_mov_b32_e32 v32, 0
	v_mov_b32_e32 v33, 0
	v_mov_b32_e32 v30, 0
	v_mov_b32_e32 v31, 0
	v_mov_b32_e32 v34, 0
	v_mov_b32_e32 v35, 0
	s_and_saveexec_b64 s[8:9], vcc
	s_cbranch_execz .LBB0_1597
	v_mov_b64_e32 v[28:29], v[150:151]
	v_mov_b64_e32 v[32:33], v[152:153]
	s_nop 0
	v_lshlrev_b32_e32 v30, 16, v28
	v_and_b32_e32 v31, 0xffff0000, v28
	v_lshlrev_b32_e32 v34, 16, v29
	v_and_b32_e32 v35, 0xffff0000, v29
	s_nop 0
	v_lshlrev_b32_e32 v28, 16, v32
	v_and_b32_e32 v29, 0xffff0000, v32
	v_lshlrev_b32_e32 v32, 16, v33
	v_and_b32_e32 v33, 0xffff0000, v33

.LBB0_2034:
	v_lshl_add_u32 v150, s38, 8, v158
	s_lshl_b32 s38, s13, 10
	v_lshl_or_b32 v148, s40, 8, v160
	s_ashr_i32 s39, s38, 31
	s_cmp_lg_u32 s13, 0
	s_cselect_b64 s[40:41], -1, 0
	s_add_u32 s4, s58, s38
	s_addc_u32 s5, s59, s39
	v_mad_u32_u24 v169, v150, s64, v148
	v_lshlrev_b32_e32 v170, 11, v150
	v_lshl_add_u32 v170, v148, 1, v170
	v_mov_b32_e32 v171, v169
	global_load_dwordx2 v[174:175], v171, s[4:5]
	global_load_dwordx2 v[176:177], v171, s[4:5] offset:128
	v_add_u32_e32 v171, 0xc000, v169
	global_load_dwordx2 v[178:179], v171, s[4:5]
	global_load_dwordx2 v[180:181], v171, s[4:5] offset:128
	v_add_u32_e32 v171, 0x18000, v169
	global_load_dwordx2 v[182:183], v171, s[4:5]
	global_load_dwordx2 v[184:185], v171, s[4:5] offset:128
	v_add_u32_e32 v171, 0x24000, v169
	global_load_dwordx2 v[186:187], v171, s[4:5]
	global_load_dwordx2 v[188:189], v171, s[4:5] offset:128
	v_add_u32_e32 v171, 0x60000, v169
	global_load_dwordx2 v[190:191], v171, s[4:5]
	global_load_dwordx2 v[192:193], v171, s[4:5] offset:128
	v_add_u32_e32 v171, 0x6c000, v169
	global_load_dwordx2 v[194:195], v171, s[4:5]
	global_load_dwordx2 v[196:197], v171, s[4:5] offset:128
	v_add_u32_e32 v171, 0x78000, v169
	global_load_dwordx2 v[198:199], v171, s[4:5]
	global_load_dwordx2 v[200:201], v171, s[4:5] offset:128
	v_add_u32_e32 v171, 0x84000, v169
	global_load_dwordx2 v[202:203], v171, s[4:5]
	global_load_dwordx2 v[204:205], v171, s[4:5] offset:128
	s_cmp_eq_u32 s13, 0
	s_cbranch_scc1 .Lbrb_z0
	v_mov_b32_e32 v172, v170
	global_load_dwordx4 v[206:209], v172, s[54:55]
	v_mov_b32_e32 v172, v170
	global_load_dwordx4 v[210:213], v172, s[54:55] offset:256
	v_add_u32_e32 v172, 0x8000, v170
	global_load_dwordx4 v[214:217], v172, s[54:55]
	v_add_u32_e32 v172, 0x8000, v170
	global_load_dwordx4 v[218:221], v172, s[54:55] offset:256
	v_add_u32_e32 v172, 0x10000, v170
	global_load_dwordx4 v[222:225], v172, s[54:55]
	s_waitcnt vmcnt(4)
	v_cvt_f32_ubyte0_e32 v128, v174
	v_cvt_f32_ubyte1_e32 v129, v174
	v_cvt_f32_ubyte2_e32 v130, v174
	v_cvt_f32_ubyte3_e32 v131, v174
	v_lshlrev_b32_e32 v164, 16, v206
	v_and_b32_e32 v165, 0xffff0000, v206
	v_lshlrev_b32_e32 v166, 16, v207
	v_and_b32_e32 v167, 0xffff0000, v207
	v_pk_mul_f32 v[128:129], v[128:129], s[16:17] op_sel_hi:[1,0]
	v_pk_mul_f32 v[130:131], v[130:131], s[16:17] op_sel_hi:[1,0]
	v_pk_fma_f32 v[124:125], v[124:125], v[128:129], v[164:165]
	v_pk_fma_f32 v[126:127], v[126:127], v[130:131], v[166:167]
	v_cvt_f32_ubyte0_e32 v128, v175
	v_cvt_f32_ubyte1_e32 v129, v175
	v_cvt_f32_ubyte2_e32 v130, v175
	v_cvt_f32_ubyte3_e32 v131, v175
	v_lshlrev_b32_e32 v164, 16, v208
	v_and_b32_e32 v165, 0xffff0000, v208
	v_lshlrev_b32_e32 v166, 16, v209
	v_and_b32_e32 v167, 0xffff0000, v209
	v_pk_mul_f32 v[128:129], v[128:129], s[16:17] op_sel_hi:[1,0]
	v_pk_mul_f32 v[130:131], v[130:131], s[16:17] op_sel_hi:[1,0]
	v_pk_fma_f32 v[120:121], v[120:121], v[128:129], v[164:165]
	v_pk_fma_f32 v[122:123], v[122:123], v[130:131], v[166:167]
	v_cvt_pk_bf16_f32 v124, v124, v125
	v_cvt_pk_bf16_f32 v125, v126, v127
	v_cvt_pk_bf16_f32 v126, v120, v121
	v_cvt_pk_bf16_f32 v127, v122, v123
	v_mov_b32_e32 v173, v170
	global_store_dwordx4 v173, v[124:127], s[54:55]
	v_add_u32_e32 v172, 0x10000, v170
	global_load_dwordx4 v[206:209], v172, s[54:55] offset:256
	s_waitcnt vmcnt(5)
	v_cvt_f32_ubyte0_e32 v128, v176
	v_cvt_f32_ubyte1_e32 v129, v176
	v_cvt_f32_ubyte2_e32 v130, v176
	v_cvt_f32_ubyte3_e32 v131, v176
	v_lshlrev_b32_e32 v164, 16, v210
	v_and_b32_e32 v165, 0xffff0000, v210
	v_lshlrev_b32_e32 v166, 16, v211
	v_and_b32_e32 v167, 0xffff0000, v211
	v_pk_mul_f32 v[128:129], v[128:129], s[16:17] op_sel_hi:[1,0]
	v_pk_mul_f32 v[130:131], v[130:131], s[16:17] op_sel_hi:[1,0]
	v_pk_fma_f32 v[116:117], v[116:117], v[128:129], v[164:165]
	v_pk_fma_f32 v[118:119], v[118:119], v[130:131], v[166:167]
	v_cvt_f32_ubyte0_e32 v128, v177
	v_cvt_f32_ubyte1_e32 v129, v177
	v_cvt_f32_ubyte2_e32 v130, v177
	v_cvt_f32_ubyte3_e32 v131, v177
	v_lshlrev_b32_e32 v164, 16, v212
	v_and_b32_e32 v165, 0xffff0000, v212
	v_lshlrev_b32_e32 v166, 16, v213
	v_and_b32_e32 v167, 0xffff0000, v213
	v_pk_mul_f32 v[128:129], v[128:129], s[16:17] op_sel_hi:[1,0]
	v_pk_mul_f32 v[130:131], v[130:131], s[16:17] op_sel_hi:[1,0]
	v_pk_fma_f32 v[112:113], v[112:113], v[128:129], v[164:165]
	v_pk_fma_f32 v[114:115], v[114:115], v[130:131], v[166:167]
	v_cvt_pk_bf16_f32 v116, v116, v117
	v_cvt_pk_bf16_f32 v117, v118, v119
	v_cvt_pk_bf16_f32 v118, v112, v113
	v_cvt_pk_bf16_f32 v119, v114, v115
	v_mov_b32_e32 v173, v170
	global_store_dwordx4 v173, v[116:119], s[54:55] offset:256
	v_add_u32_e32 v172, 0x18000, v170
	global_load_dwordx4 v[210:213], v172, s[54:55]
	s_waitcnt vmcnt(6)
	v_cvt_f32_ubyte0_e32 v128, v178
	v_cvt_f32_ubyte1_e32 v129, v178
	v_cvt_f32_ubyte2_e32 v130, v178
	v_cvt_f32_ubyte3_e32 v131, v178
	v_lshlrev_b32_e32 v164, 16, v214
	v_and_b32_e32 v165, 0xffff0000, v214
	v_lshlrev_b32_e32 v166, 16, v215
	v_and_b32_e32 v167, 0xffff0000, v215
	v_pk_mul_f32 v[128:129], v[128:129], s[16:17] op_sel_hi:[1,0]
	v_pk_mul_f32 v[130:131], v[130:131], s[16:17] op_sel_hi:[1,0]
	v_pk_fma_f32 v[108:109], v[108:109], v[128:129], v[164:165]
	v_pk_fma_f32 v[110:111], v[110:111], v[130:131], v[166:167]
	v_cvt_f32_ubyte0_e32 v128, v179
	v_cvt_f32_ubyte1_e32 v129, v179
	v_cvt_f32_ubyte2_e32 v130, v179
	v_cvt_f32_ubyte3_e32 v131, v179
	v_lshlrev_b32_e32 v164, 16, v216
	v_and_b32_e32 v165, 0xffff0000, v216
	v_lshlrev_b32_e32 v166, 16, v217
	v_and_b32_e32 v167, 0xffff0000, v217
	v_pk_mul_f32 v[128:129], v[128:129], s[16:17] op_sel_hi:[1,0]
	v_pk_mul_f32 v[130:131], v[130:131], s[16:17] op_sel_hi:[1,0]
	v_pk_fma_f32 v[104:105], v[104:105], v[128:129], v[164:165]
	v_pk_fma_f32 v[106:107], v[106:107], v[130:131], v[166:167]
	v_cvt_pk_bf16_f32 v108, v108, v109
	v_cvt_pk_bf16_f32 v109, v110, v111
	v_cvt_pk_bf16_f32 v110, v104, v105
	v_cvt_pk_bf16_f32 v111, v106, v107
	v_add_u32_e32 v173, 0x8000, v170
	global_store_dwordx4 v173, v[108:111], s[54:55]
	v_add_u32_e32 v172, 0x18000, v170
	global_load_dwordx4 v[214:217], v172, s[54:55] offset:256
	s_waitcnt vmcnt(7)
	v_cvt_f32_ubyte0_e32 v128, v180
	v_cvt_f32_ubyte1_e32 v129, v180
	v_cvt_f32_ubyte2_e32 v130, v180
	v_cvt_f32_ubyte3_e32 v131, v180
	v_lshlrev_b32_e32 v164, 16, v218
	v_and_b32_e32 v165, 0xffff0000, v218
	v_lshlrev_b32_e32 v166, 16, v219
	v_and_b32_e32 v167, 0xffff0000, v219
	v_pk_mul_f32 v[128:129], v[128:129], s[16:17] op_sel_hi:[1,0]
	v_pk_mul_f32 v[130:131], v[130:131], s[16:17] op_sel_hi:[1,0]
	v_pk_fma_f32 v[100:101], v[100:101], v[128:129], v[164:165]
	v_pk_fma_f32 v[102:103], v[102:103], v[130:131], v[166:167]
	v_cvt_f32_ubyte0_e32 v128, v181
	v_cvt_f32_ubyte1_e32 v129, v181
	v_cvt_f32_ubyte2_e32 v130, v181
	v_cvt_f32_ubyte3_e32 v131, v181
	v_lshlrev_b32_e32 v164, 16, v220
	v_and_b32_e32 v165, 0xffff0000, v220
	v_lshlrev_b32_e32 v166, 16, v221
	v_and_b32_e32 v167, 0xffff0000, v221
	v_pk_mul_f32 v[128:129], v[128:129], s[16:17] op_sel_hi:[1,0]
	v_pk_mul_f32 v[130:131], v[130:131], s[16:17] op_sel_hi:[1,0]
	v_pk_fma_f32 v[96:97], v[96:97], v[128:129], v[164:165]
	v_pk_fma_f32 v[98:99], v[98:99], v[130:131], v[166:167]
	v_cvt_pk_bf16_f32 v100, v100, v101
	v_cvt_pk_bf16_f32 v101, v102, v103
	v_cvt_pk_bf16_f32 v102, v96, v97
	v_cvt_pk_bf16_f32 v103, v98, v99
	v_add_u32_e32 v173, 0x8000, v170
	global_store_dwordx4 v173, v[100:103], s[54:55] offset:256
	v_add_u32_e32 v172, 0x40000, v170
	global_load_dwordx4 v[218:221], v172, s[54:55]
	s_waitcnt vmcnt(8)
	v_cvt_f32_ubyte0_e32 v128, v182
	v_cvt_f32_ubyte1_e32 v129, v182
	v_cvt_f32_ubyte2_e32 v130, v182
	v_cvt_f32_ubyte3_e32 v131, v182
	v_lshlrev_b32_e32 v164, 16, v222
	v_and_b32_e32 v165, 0xffff0000, v222
	v_lshlrev_b32_e32 v166, 16, v223
	v_and_b32_e32 v167, 0xffff0000, v223
	v_pk_mul_f32 v[128:129], v[128:129], s[16:17] op_sel_hi:[1,0]
	v_pk_mul_f32 v[130:131], v[130:131], s[16:17] op_sel_hi:[1,0]
	v_pk_fma_f32 v[92:93], v[92:93], v[128:129], v[164:165]
	v_pk_fma_f32 v[94:95], v[94:95], v[130:131], v[166:167]
	v_cvt_f32_ubyte0_e32 v128, v183
	v_cvt_f32_ubyte1_e32 v129, v183
	v_cvt_f32_ubyte2_e32 v130, v183
	v_cvt_f32_ubyte3_e32 v131, v183
	v_lshlrev_b32_e32 v164, 16, v224
	v_and_b32_e32 v165, 0xffff0000, v224
	v_lshlrev_b32_e32 v166, 16, v225
	v_and_b32_e32 v167, 0xffff0000, v225
	v_pk_mul_f32 v[128:129], v[128:129], s[16:17] op_sel_hi:[1,0]
	v_pk_mul_f32 v[130:131], v[130:131], s[16:17] op_sel_hi:[1,0]
	v_pk_fma_f32 v[88:89], v[88:89], v[128:129], v[164:165]
	v_pk_fma_f32 v[90:91], v[90:91], v[130:131], v[166:167]
	v_cvt_pk_bf16_f32 v92, v92, v93
	v_cvt_pk_bf16_f32 v93, v94, v95
	v_cvt_pk_bf16_f32 v94, v88, v89
	v_cvt_pk_bf16_f32 v95, v90, v91
	v_add_u32_e32 v173, 0x10000, v170
	global_store_dwordx4 v173, v[92:95], s[54:55]
	v_add_u32_e32 v172, 0x40000, v170
	global_load_dwordx4 v[222:225], v172, s[54:55] offset:256
	s_waitcnt vmcnt(8)
	v_cvt_f32_ubyte0_e32 v128, v184
	v_cvt_f32_ubyte1_e32 v129, v184
	v_cvt_f32_ubyte2_e32 v130, v184
	v_cvt_f32_ubyte3_e32 v131, v184
	v_lshlrev_b32_e32 v164, 16, v206
	v_and_b32_e32 v165, 0xffff0000, v206
	v_lshlrev_b32_e32 v166, 16, v207
	v_and_b32_e32 v167, 0xffff0000, v207
	v_pk_mul_f32 v[128:129], v[128:129], s[16:17] op_sel_hi:[1,0]
	v_pk_mul_f32 v[130:131], v[130:131], s[16:17] op_sel_hi:[1,0]
	v_pk_fma_f32 v[84:85], v[84:85], v[128:129], v[164:165]
	v_pk_fma_f32 v[86:87], v[86:87], v[130:131], v[166:167]
	v_cvt_f32_ubyte0_e32 v128, v185
	v_cvt_f32_ubyte1_e32 v129, v185
	v_cvt_f32_ubyte2_e32 v130, v185
	v_cvt_f32_ubyte3_e32 v131, v185
	v_lshlrev_b32_e32 v164, 16, v208
	v_and_b32_e32 v165, 0xffff0000, v208
	v_lshlrev_b32_e32 v166, 16, v209
	v_and_b32_e32 v167, 0xffff0000, v209
	v_pk_mul_f32 v[128:129], v[128:129], s[16:17] op_sel_hi:[1,0]
	v_pk_mul_f32 v[130:131], v[130:131], s[16:17] op_sel_hi:[1,0]
	v_pk_fma_f32 v[80:81], v[80:81], v[128:129], v[164:165]
	v_pk_fma_f32 v[82:83], v[82:83], v[130:131], v[166:167]
	v_cvt_pk_bf16_f32 v84, v84, v85
	v_cvt_pk_bf16_f32 v85, v86, v87
	v_cvt_pk_bf16_f32 v86, v80, v81
	v_cvt_pk_bf16_f32 v87, v82, v83
	v_add_u32_e32 v173, 0x10000, v170
	global_store_dwordx4 v173, v[84:87], s[54:55] offset:256
	v_add_u32_e32 v172, 0x48000, v170
	global_load_dwordx4 v[206:209], v172, s[54:55]
	s_waitcnt vmcnt(8)
	v_cvt_f32_ubyte0_e32 v128, v186
	v_cvt_f32_ubyte1_e32 v129, v186
	v_cvt_f32_ubyte2_e32 v130, v186
	v_cvt_f32_ubyte3_e32 v131, v186
	v_lshlrev_b32_e32 v164, 16, v210
	v_and_b32_e32 v165, 0xffff0000, v210
	v_lshlrev_b32_e32 v166, 16, v211
	v_and_b32_e32 v167, 0xffff0000, v211
	v_pk_mul_f32 v[128:129], v[128:129], s[16:17] op_sel_hi:[1,0]
	v_pk_mul_f32 v[130:131], v[130:131], s[16:17] op_sel_hi:[1,0]
	v_pk_fma_f32 v[76:77], v[76:77], v[128:129], v[164:165]
	v_pk_fma_f32 v[78:79], v[78:79], v[130:131], v[166:167]
	v_cvt_f32_ubyte0_e32 v128, v187
	v_cvt_f32_ubyte1_e32 v129, v187
	v_cvt_f32_ubyte2_e32 v130, v187
	v_cvt_f32_ubyte3_e32 v131, v187
	v_lshlrev_b32_e32 v164, 16, v212
	v_and_b32_e32 v165, 0xffff0000, v212
	v_lshlrev_b32_e32 v166, 16, v213
	v_and_b32_e32 v167, 0xffff0000, v213
	v_pk_mul_f32 v[128:129], v[128:129], s[16:17] op_sel_hi:[1,0]
	v_pk_mul_f32 v[130:131], v[130:131], s[16:17] op_sel_hi:[1,0]
	v_pk_fma_f32 v[72:73], v[72:73], v[128:129], v[164:165]
	v_pk_fma_f32 v[74:75], v[74:75], v[130:131], v[166:167]
	v_cvt_pk_bf16_f32 v76, v76, v77
	v_cvt_pk_bf16_f32 v77, v78, v79
	v_cvt_pk_bf16_f32 v78, v72, v73
	v_cvt_pk_bf16_f32 v79, v74, v75
	v_add_u32_e32 v173, 0x18000, v170
	global_store_dwordx4 v173, v[76:79], s[54:55]
	v_add_u32_e32 v172, 0x48000, v170
	global_load_dwordx4 v[210:213], v172, s[54:55] offset:256
	s_waitcnt vmcnt(8)
	v_cvt_f32_ubyte0_e32 v128, v188
	v_cvt_f32_ubyte1_e32 v129, v188
	v_cvt_f32_ubyte2_e32 v130, v188
	v_cvt_f32_ubyte3_e32 v131, v188
	v_lshlrev_b32_e32 v164, 16, v214
	v_and_b32_e32 v165, 0xffff0000, v214
	v_lshlrev_b32_e32 v166, 16, v215
	v_and_b32_e32 v167, 0xffff0000, v215
	v_pk_mul_f32 v[128:129], v[128:129], s[16:17] op_sel_hi:[1,0]
	v_pk_mul_f32 v[130:131], v[130:131], s[16:17] op_sel_hi:[1,0]
	v_pk_fma_f32 v[68:69], v[68:69], v[128:129], v[164:165]
	v_pk_fma_f32 v[70:71], v[70:71], v[130:131], v[166:167]
	v_cvt_f32_ubyte0_e32 v128, v189
	v_cvt_f32_ubyte1_e32 v129, v189
	v_cvt_f32_ubyte2_e32 v130, v189
	v_cvt_f32_ubyte3_e32 v131, v189
	v_lshlrev_b32_e32 v164, 16, v216
	v_and_b32_e32 v165, 0xffff0000, v216
	v_lshlrev_b32_e32 v166, 16, v217
	v_and_b32_e32 v167, 0xffff0000, v217
	v_pk_mul_f32 v[128:129], v[128:129], s[16:17] op_sel_hi:[1,0]
	v_pk_mul_f32 v[130:131], v[130:131], s[16:17] op_sel_hi:[1,0]
	v_pk_fma_f32 v[64:65], v[64:65], v[128:129], v[164:165]
	v_pk_fma_f32 v[66:67], v[66:67], v[130:131], v[166:167]
	v_cvt_pk_bf16_f32 v68, v68, v69
	v_cvt_pk_bf16_f32 v69, v70, v71
	v_cvt_pk_bf16_f32 v70, v64, v65
	v_cvt_pk_bf16_f32 v71, v66, v67
	v_add_u32_e32 v173, 0x18000, v170
	global_store_dwordx4 v173, v[68:71], s[54:55] offset:256
	v_add_u32_e32 v172, 0x50000, v170
	global_load_dwordx4 v[214:217], v172, s[54:55]
	s_waitcnt vmcnt(8)
	v_cvt_f32_ubyte0_e32 v128, v190
	v_cvt_f32_ubyte1_e32 v129, v190
	v_cvt_f32_ubyte2_e32 v130, v190
	v_cvt_f32_ubyte3_e32 v131, v190
	v_lshlrev_b32_e32 v164, 16, v218
	v_and_b32_e32 v165, 0xffff0000, v218
	v_lshlrev_b32_e32 v166, 16, v219
	v_and_b32_e32 v167, 0xffff0000, v219
	v_pk_mul_f32 v[128:129], v[128:129], s[16:17] op_sel_hi:[1,0]
	v_pk_mul_f32 v[130:131], v[130:131], s[16:17] op_sel_hi:[1,0]
	v_pk_fma_f32 v[60:61], v[60:61], v[128:129], v[164:165]
	v_pk_fma_f32 v[62:63], v[62:63], v[130:131], v[166:167]
	v_cvt_f32_ubyte0_e32 v128, v191
	v_cvt_f32_ubyte1_e32 v129, v191
	v_cvt_f32_ubyte2_e32 v130, v191
	v_cvt_f32_ubyte3_e32 v131, v191
	v_lshlrev_b32_e32 v164, 16, v220
	v_and_b32_e32 v165, 0xffff0000, v220
	v_lshlrev_b32_e32 v166, 16, v221
	v_and_b32_e32 v167, 0xffff0000, v221
	v_pk_mul_f32 v[128:129], v[128:129], s[16:17] op_sel_hi:[1,0]
	v_pk_mul_f32 v[130:131], v[130:131], s[16:17] op_sel_hi:[1,0]
	v_pk_fma_f32 v[56:57], v[56:57], v[128:129], v[164:165]
	v_pk_fma_f32 v[58:59], v[58:59], v[130:131], v[166:167]
	v_cvt_pk_bf16_f32 v60, v60, v61
	v_cvt_pk_bf16_f32 v61, v62, v63
	v_cvt_pk_bf16_f32 v62, v56, v57
	v_cvt_pk_bf16_f32 v63, v58, v59
	v_add_u32_e32 v173, 0x40000, v170
	global_store_dwordx4 v173, v[60:63], s[54:55]
	v_add_u32_e32 v172, 0x50000, v170
	global_load_dwordx4 v[218:221], v172, s[54:55] offset:256
	s_waitcnt vmcnt(8)
	v_cvt_f32_ubyte0_e32 v128, v192
	v_cvt_f32_ubyte1_e32 v129, v192
	v_cvt_f32_ubyte2_e32 v130, v192
	v_cvt_f32_ubyte3_e32 v131, v192
	v_lshlrev_b32_e32 v164, 16, v222
	v_and_b32_e32 v165, 0xffff0000, v222
	v_lshlrev_b32_e32 v166, 16, v223
	v_and_b32_e32 v167, 0xffff0000, v223
	v_pk_mul_f32 v[128:129], v[128:129], s[16:17] op_sel_hi:[1,0]
	v_pk_mul_f32 v[130:131], v[130:131], s[16:17] op_sel_hi:[1,0]
	v_pk_fma_f32 v[52:53], v[52:53], v[128:129], v[164:165]
	v_pk_fma_f32 v[54:55], v[54:55], v[130:131], v[166:167]
	v_cvt_f32_ubyte0_e32 v128, v193
	v_cvt_f32_ubyte1_e32 v129, v193
	v_cvt_f32_ubyte2_e32 v130, v193
	v_cvt_f32_ubyte3_e32 v131, v193
	v_lshlrev_b32_e32 v164, 16, v224
	v_and_b32_e32 v165, 0xffff0000, v224
	v_lshlrev_b32_e32 v166, 16, v225
	v_and_b32_e32 v167, 0xffff0000, v225
	v_pk_mul_f32 v[128:129], v[128:129], s[16:17] op_sel_hi:[1,0]
	v_pk_mul_f32 v[130:131], v[130:131], s[16:17] op_sel_hi:[1,0]
	v_pk_fma_f32 v[48:49], v[48:49], v[128:129], v[164:165]
	v_pk_fma_f32 v[50:51], v[50:51], v[130:131], v[166:167]
	v_cvt_pk_bf16_f32 v52, v52, v53
	v_cvt_pk_bf16_f32 v53, v54, v55
	v_cvt_pk_bf16_f32 v54, v48, v49
	v_cvt_pk_bf16_f32 v55, v50, v51
	v_add_u32_e32 v173, 0x40000, v170
	global_store_dwordx4 v173, v[52:55], s[54:55] offset:256
	v_add_u32_e32 v172, 0x58000, v170
	global_load_dwordx4 v[222:225], v172, s[54:55]
	s_waitcnt vmcnt(8)
	v_cvt_f32_ubyte0_e32 v128, v194
	v_cvt_f32_ubyte1_e32 v129, v194
	v_cvt_f32_ubyte2_e32 v130, v194
	v_cvt_f32_ubyte3_e32 v131, v194
	v_lshlrev_b32_e32 v164, 16, v206
	v_and_b32_e32 v165, 0xffff0000, v206
	v_lshlrev_b32_e32 v166, 16, v207
	v_and_b32_e32 v167, 0xffff0000, v207
	v_pk_mul_f32 v[128:129], v[128:129], s[16:17] op_sel_hi:[1,0]
	v_pk_mul_f32 v[130:131], v[130:131], s[16:17] op_sel_hi:[1,0]
	v_pk_fma_f32 v[44:45], v[44:45], v[128:129], v[164:165]
	v_pk_fma_f32 v[46:47], v[46:47], v[130:131], v[166:167]
	v_cvt_f32_ubyte0_e32 v128, v195
	v_cvt_f32_ubyte1_e32 v129, v195
	v_cvt_f32_ubyte2_e32 v130, v195
	v_cvt_f32_ubyte3_e32 v131, v195
	v_lshlrev_b32_e32 v164, 16, v208
	v_and_b32_e32 v165, 0xffff0000, v208
	v_lshlrev_b32_e32 v166, 16, v209
	v_and_b32_e32 v167, 0xffff0000, v209
	v_pk_mul_f32 v[128:129], v[128:129], s[16:17] op_sel_hi:[1,0]
	v_pk_mul_f32 v[130:131], v[130:131], s[16:17] op_sel_hi:[1,0]
	v_pk_fma_f32 v[40:41], v[40:41], v[128:129], v[164:165]
	v_pk_fma_f32 v[42:43], v[42:43], v[130:131], v[166:167]
	v_cvt_pk_bf16_f32 v44, v44, v45
	v_cvt_pk_bf16_f32 v45, v46, v47
	v_cvt_pk_bf16_f32 v46, v40, v41
	v_cvt_pk_bf16_f32 v47, v42, v43
	v_add_u32_e32 v173, 0x48000, v170
	global_store_dwordx4 v173, v[44:47], s[54:55]
	v_add_u32_e32 v172, 0x58000, v170
	global_load_dwordx4 v[206:209], v172, s[54:55] offset:256
	s_waitcnt vmcnt(8)
	v_cvt_f32_ubyte0_e32 v128, v196
	v_cvt_f32_ubyte1_e32 v129, v196
	v_cvt_f32_ubyte2_e32 v130, v196
	v_cvt_f32_ubyte3_e32 v131, v196
	v_lshlrev_b32_e32 v164, 16, v210
	v_and_b32_e32 v165, 0xffff0000, v210
	v_lshlrev_b32_e32 v166, 16, v211
	v_and_b32_e32 v167, 0xffff0000, v211
	v_pk_mul_f32 v[128:129], v[128:129], s[16:17] op_sel_hi:[1,0]
	v_pk_mul_f32 v[130:131], v[130:131], s[16:17] op_sel_hi:[1,0]
	v_pk_fma_f32 v[36:37], v[36:37], v[128:129], v[164:165]
	v_pk_fma_f32 v[38:39], v[38:39], v[130:131], v[166:167]
	v_cvt_f32_ubyte0_e32 v128, v197
	v_cvt_f32_ubyte1_e32 v129, v197
	v_cvt_f32_ubyte2_e32 v130, v197
	v_cvt_f32_ubyte3_e32 v131, v197
	v_lshlrev_b32_e32 v164, 16, v212
	v_and_b32_e32 v165, 0xffff0000, v212
	v_lshlrev_b32_e32 v166, 16, v213
	v_and_b32_e32 v167, 0xffff0000, v213
	v_pk_mul_f32 v[128:129], v[128:129], s[16:17] op_sel_hi:[1,0]
	v_pk_mul_f32 v[130:131], v[130:131], s[16:17] op_sel_hi:[1,0]
	v_pk_fma_f32 v[32:33], v[32:33], v[128:129], v[164:165]
	v_pk_fma_f32 v[34:35], v[34:35], v[130:131], v[166:167]
	v_cvt_pk_bf16_f32 v36, v36, v37
	v_cvt_pk_bf16_f32 v37, v38, v39
	v_cvt_pk_bf16_f32 v38, v32, v33
	v_cvt_pk_bf16_f32 v39, v34, v35
	v_add_u32_e32 v173, 0x48000, v170
	global_store_dwordx4 v173, v[36:39], s[54:55] offset:256
	s_waitcnt vmcnt(7)
	v_cvt_f32_ubyte0_e32 v128, v198
	v_cvt_f32_ubyte1_e32 v129, v198
	v_cvt_f32_ubyte2_e32 v130, v198
	v_cvt_f32_ubyte3_e32 v131, v198
	v_lshlrev_b32_e32 v164, 16, v214
	v_and_b32_e32 v165, 0xffff0000, v214
	v_lshlrev_b32_e32 v166, 16, v215
	v_and_b32_e32 v167, 0xffff0000, v215
	v_pk_mul_f32 v[128:129], v[128:129], s[16:17] op_sel_hi:[1,0]
	v_pk_mul_f32 v[130:131], v[130:131], s[16:17] op_sel_hi:[1,0]
	v_pk_fma_f32 v[28:29], v[28:29], v[128:129], v[164:165]
	v_pk_fma_f32 v[30:31], v[30:31], v[130:131], v[166:167]
	v_cvt_f32_ubyte0_e32 v128, v199
	v_cvt_f32_ubyte1_e32 v129, v199
	v_cvt_f32_ubyte2_e32 v130, v199
	v_cvt_f32_ubyte3_e32 v131, v199
	v_lshlrev_b32_e32 v164, 16, v216
	v_and_b32_e32 v165, 0xffff0000, v216
	v_lshlrev_b32_e32 v166, 16, v217
	v_and_b32_e32 v167, 0xffff0000, v217
	v_pk_mul_f32 v[128:129], v[128:129], s[16:17] op_sel_hi:[1,0]
	v_pk_mul_f32 v[130:131], v[130:131], s[16:17] op_sel_hi:[1,0]
	v_pk_fma_f32 v[24:25], v[24:25], v[128:129], v[164:165]
	v_pk_fma_f32 v[26:27], v[26:27], v[130:131], v[166:167]
	v_cvt_pk_bf16_f32 v28, v28, v29
	v_cvt_pk_bf16_f32 v29, v30, v31
	v_cvt_pk_bf16_f32 v30, v24, v25
	v_cvt_pk_bf16_f32 v31, v26, v27
	v_add_u32_e32 v173, 0x50000, v170
	global_store_dwordx4 v173, v[28:31], s[54:55]
	s_waitcnt vmcnt(6)
	v_cvt_f32_ubyte0_e32 v128, v200
	v_cvt_f32_ubyte1_e32 v129, v200
	v_cvt_f32_ubyte2_e32 v130, v200
	v_cvt_f32_ubyte3_e32 v131, v200
	v_lshlrev_b32_e32 v164, 16, v218
	v_and_b32_e32 v165, 0xffff0000, v218
	v_lshlrev_b32_e32 v166, 16, v219
	v_and_b32_e32 v167, 0xffff0000, v219
	v_pk_mul_f32 v[128:129], v[128:129], s[16:17] op_sel_hi:[1,0]
	v_pk_mul_f32 v[130:131], v[130:131], s[16:17] op_sel_hi:[1,0]
	v_pk_fma_f32 v[20:21], v[20:21], v[128:129], v[164:165]
	v_pk_fma_f32 v[22:23], v[22:23], v[130:131], v[166:167]
	v_cvt_f32_ubyte0_e32 v128, v201
	v_cvt_f32_ubyte1_e32 v129, v201
	v_cvt_f32_ubyte2_e32 v130, v201
	v_cvt_f32_ubyte3_e32 v131, v201
	v_lshlrev_b32_e32 v164, 16, v220
	v_and_b32_e32 v165, 0xffff0000, v220
	v_lshlrev_b32_e32 v166, 16, v221
	v_and_b32_e32 v167, 0xffff0000, v221
	v_pk_mul_f32 v[128:129], v[128:129], s[16:17] op_sel_hi:[1,0]
	v_pk_mul_f32 v[130:131], v[130:131], s[16:17] op_sel_hi:[1,0]
	v_pk_fma_f32 v[16:17], v[16:17], v[128:129], v[164:165]
	v_pk_fma_f32 v[18:19], v[18:19], v[130:131], v[166:167]
	v_cvt_pk_bf16_f32 v20, v20, v21
	v_cvt_pk_bf16_f32 v21, v22, v23
	v_cvt_pk_bf16_f32 v22, v16, v17
	v_cvt_pk_bf16_f32 v23, v18, v19
	v_add_u32_e32 v173, 0x50000, v170
	global_store_dwordx4 v173, v[20:23], s[54:55] offset:256
	s_waitcnt vmcnt(5)
	v_cvt_f32_ubyte0_e32 v128, v202
	v_cvt_f32_ubyte1_e32 v129, v202
	v_cvt_f32_ubyte2_e32 v130, v202
	v_cvt_f32_ubyte3_e32 v131, v202
	v_lshlrev_b32_e32 v164, 16, v222
	v_and_b32_e32 v165, 0xffff0000, v222
	v_lshlrev_b32_e32 v166, 16, v223
	v_and_b32_e32 v167, 0xffff0000, v223
	v_pk_mul_f32 v[128:129], v[128:129], s[16:17] op_sel_hi:[1,0]
	v_pk_mul_f32 v[130:131], v[130:131], s[16:17] op_sel_hi:[1,0]
	v_pk_fma_f32 v[12:13], v[12:13], v[128:129], v[164:165]
	v_pk_fma_f32 v[14:15], v[14:15], v[130:131], v[166:167]
	v_cvt_f32_ubyte0_e32 v128, v203
	v_cvt_f32_ubyte1_e32 v129, v203
	v_cvt_f32_ubyte2_e32 v130, v203
	v_cvt_f32_ubyte3_e32 v131, v203
	v_lshlrev_b32_e32 v164, 16, v224
	v_and_b32_e32 v165, 0xffff0000, v224
	v_lshlrev_b32_e32 v166, 16, v225
	v_and_b32_e32 v167, 0xffff0000, v225
	v_pk_mul_f32 v[128:129], v[128:129], s[16:17] op_sel_hi:[1,0]
	v_pk_mul_f32 v[130:131], v[130:131], s[16:17] op_sel_hi:[1,0]
	v_pk_fma_f32 v[8:9], v[8:9], v[128:129], v[164:165]
	v_pk_fma_f32 v[10:11], v[10:11], v[130:131], v[166:167]
	v_cvt_pk_bf16_f32 v12, v12, v13
	v_cvt_pk_bf16_f32 v13, v14, v15
	v_cvt_pk_bf16_f32 v14, v8, v9
	v_cvt_pk_bf16_f32 v15, v10, v11
	v_add_u32_e32 v173, 0x58000, v170
	global_store_dwordx4 v173, v[12:15], s[54:55]
	s_waitcnt vmcnt(4)
	v_cvt_f32_ubyte0_e32 v128, v204
	v_cvt_f32_ubyte1_e32 v129, v204
	v_cvt_f32_ubyte2_e32 v130, v204
	v_cvt_f32_ubyte3_e32 v131, v204
	v_lshlrev_b32_e32 v164, 16, v206
	v_and_b32_e32 v165, 0xffff0000, v206
	v_lshlrev_b32_e32 v166, 16, v207
	v_and_b32_e32 v167, 0xffff0000, v207
	v_pk_mul_f32 v[128:129], v[128:129], s[16:17] op_sel_hi:[1,0]
	v_pk_mul_f32 v[130:131], v[130:131], s[16:17] op_sel_hi:[1,0]
	v_pk_fma_f32 v[4:5], v[4:5], v[128:129], v[164:165]
	v_pk_fma_f32 v[6:7], v[6:7], v[130:131], v[166:167]
	v_cvt_f32_ubyte0_e32 v128, v205
	v_cvt_f32_ubyte1_e32 v129, v205
	v_cvt_f32_ubyte2_e32 v130, v205
	v_cvt_f32_ubyte3_e32 v131, v205
	v_lshlrev_b32_e32 v164, 16, v208
	v_and_b32_e32 v165, 0xffff0000, v208
	v_lshlrev_b32_e32 v166, 16, v209
	v_and_b32_e32 v167, 0xffff0000, v209
	v_pk_mul_f32 v[128:129], v[128:129], s[16:17] op_sel_hi:[1,0]
	v_pk_mul_f32 v[130:131], v[130:131], s[16:17] op_sel_hi:[1,0]
	v_pk_fma_f32 v[0:1], v[0:1], v[128:129], v[164:165]
	v_pk_fma_f32 v[2:3], v[2:3], v[130:131], v[166:167]
	v_cvt_pk_bf16_f32 v4, v4, v5
	v_cvt_pk_bf16_f32 v5, v6, v7
	v_cvt_pk_bf16_f32 v6, v0, v1
	v_cvt_pk_bf16_f32 v7, v2, v3
	v_add_u32_e32 v173, 0x58000, v170
	global_store_dwordx4 v173, v[4:7], s[54:55] offset:256
	s_branch .Lbrb_end
.Lbrb_z0:
	v_mov_b32_e32 v154, 0
	v_mov_b32_e32 v155, 0
	s_waitcnt vmcnt(0)
	v_cvt_f32_ubyte0_e32 v128, v174
	v_cvt_f32_ubyte1_e32 v129, v174
	v_cvt_f32_ubyte2_e32 v130, v174
	v_cvt_f32_ubyte3_e32 v131, v174
	v_pk_mul_f32 v[128:129], v[128:129], s[16:17] op_sel_hi:[1,0]
	v_pk_mul_f32 v[130:131], v[130:131], s[16:17] op_sel_hi:[1,0]
	v_pk_fma_f32 v[124:125], v[124:125], v[128:129], v[154:155]
	v_pk_fma_f32 v[126:127], v[126:127], v[130:131], v[154:155]
	v_cvt_f32_ubyte0_e32 v128, v175
	v_cvt_f32_ubyte1_e32 v129, v175
	v_cvt_f32_ubyte2_e32 v130, v175
	v_cvt_f32_ubyte3_e32 v131, v175
	v_pk_mul_f32 v[128:129], v[128:129], s[16:17] op_sel_hi:[1,0]
	v_pk_mul_f32 v[130:131], v[130:131], s[16:17] op_sel_hi:[1,0]
	v_pk_fma_f32 v[120:121], v[120:121], v[128:129], v[154:155]
	v_pk_fma_f32 v[122:123], v[122:123], v[130:131], v[154:155]
	v_cvt_pk_bf16_f32 v124, v124, v125
	v_cvt_pk_bf16_f32 v125, v126, v127
	v_cvt_pk_bf16_f32 v126, v120, v121
	v_cvt_pk_bf16_f32 v127, v122, v123
	v_mov_b32_e32 v173, v170
	global_store_dwordx4 v173, v[124:127], s[54:55]
	v_cvt_f32_ubyte0_e32 v128, v176
	v_cvt_f32_ubyte1_e32 v129, v176
	v_cvt_f32_ubyte2_e32 v130, v176
	v_cvt_f32_ubyte3_e32 v131, v176
	v_pk_mul_f32 v[128:129], v[128:129], s[16:17] op_sel_hi:[1,0]
	v_pk_mul_f32 v[130:131], v[130:131], s[16:17] op_sel_hi:[1,0]
	v_pk_fma_f32 v[116:117], v[116:117], v[128:129], v[154:155]
	v_pk_fma_f32 v[118:119], v[118:119], v[130:131], v[154:155]
	v_cvt_f32_ubyte0_e32 v128, v177
	v_cvt_f32_ubyte1_e32 v129, v177
	v_cvt_f32_ubyte2_e32 v130, v177
	v_cvt_f32_ubyte3_e32 v131, v177
	v_pk_mul_f32 v[128:129], v[128:129], s[16:17] op_sel_hi:[1,0]
	v_pk_mul_f32 v[130:131], v[130:131], s[16:17] op_sel_hi:[1,0]
	v_pk_fma_f32 v[112:113], v[112:113], v[128:129], v[154:155]
	v_pk_fma_f32 v[114:115], v[114:115], v[130:131], v[154:155]
	v_cvt_pk_bf16_f32 v116, v116, v117
	v_cvt_pk_bf16_f32 v117, v118, v119
	v_cvt_pk_bf16_f32 v118, v112, v113
	v_cvt_pk_bf16_f32 v119, v114, v115
	v_mov_b32_e32 v173, v170
	global_store_dwordx4 v173, v[116:119], s[54:55] offset:256
	v_cvt_f32_ubyte0_e32 v128, v178
	v_cvt_f32_ubyte1_e32 v129, v178
	v_cvt_f32_ubyte2_e32 v130, v178
	v_cvt_f32_ubyte3_e32 v131, v178
	v_pk_mul_f32 v[128:129], v[128:129], s[16:17] op_sel_hi:[1,0]
	v_pk_mul_f32 v[130:131], v[130:131], s[16:17] op_sel_hi:[1,0]
	v_pk_fma_f32 v[108:109], v[108:109], v[128:129], v[154:155]
	v_pk_fma_f32 v[110:111], v[110:111], v[130:131], v[154:155]
	v_cvt_f32_ubyte0_e32 v128, v179
	v_cvt_f32_ubyte1_e32 v129, v179
	v_cvt_f32_ubyte2_e32 v130, v179
	v_cvt_f32_ubyte3_e32 v131, v179
	v_pk_mul_f32 v[128:129], v[128:129], s[16:17] op_sel_hi:[1,0]
	v_pk_mul_f32 v[130:131], v[130:131], s[16:17] op_sel_hi:[1,0]
	v_pk_fma_f32 v[104:105], v[104:105], v[128:129], v[154:155]
	v_pk_fma_f32 v[106:107], v[106:107], v[130:131], v[154:155]
	v_cvt_pk_bf16_f32 v108, v108, v109
	v_cvt_pk_bf16_f32 v109, v110, v111
	v_cvt_pk_bf16_f32 v110, v104, v105
	v_cvt_pk_bf16_f32 v111, v106, v107
	v_add_u32_e32 v173, 0x8000, v170
	global_store_dwordx4 v173, v[108:111], s[54:55]
	v_cvt_f32_ubyte0_e32 v128, v180
	v_cvt_f32_ubyte1_e32 v129, v180
	v_cvt_f32_ubyte2_e32 v130, v180
	v_cvt_f32_ubyte3_e32 v131, v180
	v_pk_mul_f32 v[128:129], v[128:129], s[16:17] op_sel_hi:[1,0]
	v_pk_mul_f32 v[130:131], v[130:131], s[16:17] op_sel_hi:[1,0]
	v_pk_fma_f32 v[100:101], v[100:101], v[128:129], v[154:155]
	v_pk_fma_f32 v[102:103], v[102:103], v[130:131], v[154:155]
	v_cvt_f32_ubyte0_e32 v128, v181
	v_cvt_f32_ubyte1_e32 v129, v181
	v_cvt_f32_ubyte2_e32 v130, v181
	v_cvt_f32_ubyte3_e32 v131, v181
	v_pk_mul_f32 v[128:129], v[128:129], s[16:17] op_sel_hi:[1,0]
	v_pk_mul_f32 v[130:131], v[130:131], s[16:17] op_sel_hi:[1,0]
	v_pk_fma_f32 v[96:97], v[96:97], v[128:129], v[154:155]
	v_pk_fma_f32 v[98:99], v[98:99], v[130:131], v[154:155]
	v_cvt_pk_bf16_f32 v100, v100, v101
	v_cvt_pk_bf16_f32 v101, v102, v103
	v_cvt_pk_bf16_f32 v102, v96, v97
	v_cvt_pk_bf16_f32 v103, v98, v99
	v_add_u32_e32 v173, 0x8000, v170
	global_store_dwordx4 v173, v[100:103], s[54:55] offset:256
	v_cvt_f32_ubyte0_e32 v128, v182
	v_cvt_f32_ubyte1_e32 v129, v182
	v_cvt_f32_ubyte2_e32 v130, v182
	v_cvt_f32_ubyte3_e32 v131, v182
	v_pk_mul_f32 v[128:129], v[128:129], s[16:17] op_sel_hi:[1,0]
	v_pk_mul_f32 v[130:131], v[130:131], s[16:17] op_sel_hi:[1,0]
	v_pk_fma_f32 v[92:93], v[92:93], v[128:129], v[154:155]
	v_pk_fma_f32 v[94:95], v[94:95], v[130:131], v[154:155]
	v_cvt_f32_ubyte0_e32 v128, v183
	v_cvt_f32_ubyte1_e32 v129, v183
	v_cvt_f32_ubyte2_e32 v130, v183
	v_cvt_f32_ubyte3_e32 v131, v183
	v_pk_mul_f32 v[128:129], v[128:129], s[16:17] op_sel_hi:[1,0]
	v_pk_mul_f32 v[130:131], v[130:131], s[16:17] op_sel_hi:[1,0]
	v_pk_fma_f32 v[88:89], v[88:89], v[128:129], v[154:155]
	v_pk_fma_f32 v[90:91], v[90:91], v[130:131], v[154:155]
	v_cvt_pk_bf16_f32 v92, v92, v93
	v_cvt_pk_bf16_f32 v93, v94, v95
	v_cvt_pk_bf16_f32 v94, v88, v89
	v_cvt_pk_bf16_f32 v95, v90, v91
	v_add_u32_e32 v173, 0x10000, v170
	global_store_dwordx4 v173, v[92:95], s[54:55]
	v_cvt_f32_ubyte0_e32 v128, v184
	v_cvt_f32_ubyte1_e32 v129, v184
	v_cvt_f32_ubyte2_e32 v130, v184
	v_cvt_f32_ubyte3_e32 v131, v184
	v_pk_mul_f32 v[128:129], v[128:129], s[16:17] op_sel_hi:[1,0]
	v_pk_mul_f32 v[130:131], v[130:131], s[16:17] op_sel_hi:[1,0]
	v_pk_fma_f32 v[84:85], v[84:85], v[128:129], v[154:155]
	v_pk_fma_f32 v[86:87], v[86:87], v[130:131], v[154:155]
	v_cvt_f32_ubyte0_e32 v128, v185
	v_cvt_f32_ubyte1_e32 v129, v185
	v_cvt_f32_ubyte2_e32 v130, v185
	v_cvt_f32_ubyte3_e32 v131, v185
	v_pk_mul_f32 v[128:129], v[128:129], s[16:17] op_sel_hi:[1,0]
	v_pk_mul_f32 v[130:131], v[130:131], s[16:17] op_sel_hi:[1,0]
	v_pk_fma_f32 v[80:81], v[80:81], v[128:129], v[154:155]
	v_pk_fma_f32 v[82:83], v[82:83], v[130:131], v[154:155]
	v_cvt_pk_bf16_f32 v84, v84, v85
	v_cvt_pk_bf16_f32 v85, v86, v87
	v_cvt_pk_bf16_f32 v86, v80, v81
	v_cvt_pk_bf16_f32 v87, v82, v83
	v_add_u32_e32 v173, 0x10000, v170
	global_store_dwordx4 v173, v[84:87], s[54:55] offset:256
	v_cvt_f32_ubyte0_e32 v128, v186
	v_cvt_f32_ubyte1_e32 v129, v186
	v_cvt_f32_ubyte2_e32 v130, v186
	v_cvt_f32_ubyte3_e32 v131, v186
	v_pk_mul_f32 v[128:129], v[128:129], s[16:17] op_sel_hi:[1,0]
	v_pk_mul_f32 v[130:131], v[130:131], s[16:17] op_sel_hi:[1,0]
	v_pk_fma_f32 v[76:77], v[76:77], v[128:129], v[154:155]
	v_pk_fma_f32 v[78:79], v[78:79], v[130:131], v[154:155]
	v_cvt_f32_ubyte0_e32 v128, v187
	v_cvt_f32_ubyte1_e32 v129, v187
	v_cvt_f32_ubyte2_e32 v130, v187
	v_cvt_f32_ubyte3_e32 v131, v187
	v_pk_mul_f32 v[128:129], v[128:129], s[16:17] op_sel_hi:[1,0]
	v_pk_mul_f32 v[130:131], v[130:131], s[16:17] op_sel_hi:[1,0]
	v_pk_fma_f32 v[72:73], v[72:73], v[128:129], v[154:155]
	v_pk_fma_f32 v[74:75], v[74:75], v[130:131], v[154:155]
	v_cvt_pk_bf16_f32 v76, v76, v77
	v_cvt_pk_bf16_f32 v77, v78, v79
	v_cvt_pk_bf16_f32 v78, v72, v73
	v_cvt_pk_bf16_f32 v79, v74, v75
	v_add_u32_e32 v173, 0x18000, v170
	global_store_dwordx4 v173, v[76:79], s[54:55]
	v_cvt_f32_ubyte0_e32 v128, v188
	v_cvt_f32_ubyte1_e32 v129, v188
	v_cvt_f32_ubyte2_e32 v130, v188
	v_cvt_f32_ubyte3_e32 v131, v188
	v_pk_mul_f32 v[128:129], v[128:129], s[16:17] op_sel_hi:[1,0]
	v_pk_mul_f32 v[130:131], v[130:131], s[16:17] op_sel_hi:[1,0]
	v_pk_fma_f32 v[68:69], v[68:69], v[128:129], v[154:155]
	v_pk_fma_f32 v[70:71], v[70:71], v[130:131], v[154:155]
	v_cvt_f32_ubyte0_e32 v128, v189
	v_cvt_f32_ubyte1_e32 v129, v189
	v_cvt_f32_ubyte2_e32 v130, v189
	v_cvt_f32_ubyte3_e32 v131, v189
	v_pk_mul_f32 v[128:129], v[128:129], s[16:17] op_sel_hi:[1,0]
	v_pk_mul_f32 v[130:131], v[130:131], s[16:17] op_sel_hi:[1,0]
	v_pk_fma_f32 v[64:65], v[64:65], v[128:129], v[154:155]
	v_pk_fma_f32 v[66:67], v[66:67], v[130:131], v[154:155]
	v_cvt_pk_bf16_f32 v68, v68, v69
	v_cvt_pk_bf16_f32 v69, v70, v71
	v_cvt_pk_bf16_f32 v70, v64, v65
	v_cvt_pk_bf16_f32 v71, v66, v67
	v_add_u32_e32 v173, 0x18000, v170
	global_store_dwordx4 v173, v[68:71], s[54:55] offset:256
	v_cvt_f32_ubyte0_e32 v128, v190
	v_cvt_f32_ubyte1_e32 v129, v190
	v_cvt_f32_ubyte2_e32 v130, v190
	v_cvt_f32_ubyte3_e32 v131, v190
	v_pk_mul_f32 v[128:129], v[128:129], s[16:17] op_sel_hi:[1,0]
	v_pk_mul_f32 v[130:131], v[130:131], s[16:17] op_sel_hi:[1,0]
	v_pk_fma_f32 v[60:61], v[60:61], v[128:129], v[154:155]
	v_pk_fma_f32 v[62:63], v[62:63], v[130:131], v[154:155]
	v_cvt_f32_ubyte0_e32 v128, v191
	v_cvt_f32_ubyte1_e32 v129, v191
	v_cvt_f32_ubyte2_e32 v130, v191
	v_cvt_f32_ubyte3_e32 v131, v191
	v_pk_mul_f32 v[128:129], v[128:129], s[16:17] op_sel_hi:[1,0]
	v_pk_mul_f32 v[130:131], v[130:131], s[16:17] op_sel_hi:[1,0]
	v_pk_fma_f32 v[56:57], v[56:57], v[128:129], v[154:155]
	v_pk_fma_f32 v[58:59], v[58:59], v[130:131], v[154:155]
	v_cvt_pk_bf16_f32 v60, v60, v61
	v_cvt_pk_bf16_f32 v61, v62, v63
	v_cvt_pk_bf16_f32 v62, v56, v57
	v_cvt_pk_bf16_f32 v63, v58, v59
	v_add_u32_e32 v173, 0x40000, v170
	global_store_dwordx4 v173, v[60:63], s[54:55]
	v_cvt_f32_ubyte0_e32 v128, v192
	v_cvt_f32_ubyte1_e32 v129, v192
	v_cvt_f32_ubyte2_e32 v130, v192
	v_cvt_f32_ubyte3_e32 v131, v192
	v_pk_mul_f32 v[128:129], v[128:129], s[16:17] op_sel_hi:[1,0]
	v_pk_mul_f32 v[130:131], v[130:131], s[16:17] op_sel_hi:[1,0]
	v_pk_fma_f32 v[52:53], v[52:53], v[128:129], v[154:155]
	v_pk_fma_f32 v[54:55], v[54:55], v[130:131], v[154:155]
	v_cvt_f32_ubyte0_e32 v128, v193
	v_cvt_f32_ubyte1_e32 v129, v193
	v_cvt_f32_ubyte2_e32 v130, v193
	v_cvt_f32_ubyte3_e32 v131, v193
	v_pk_mul_f32 v[128:129], v[128:129], s[16:17] op_sel_hi:[1,0]
	v_pk_mul_f32 v[130:131], v[130:131], s[16:17] op_sel_hi:[1,0]
	v_pk_fma_f32 v[48:49], v[48:49], v[128:129], v[154:155]
	v_pk_fma_f32 v[50:51], v[50:51], v[130:131], v[154:155]
	v_cvt_pk_bf16_f32 v52, v52, v53
	v_cvt_pk_bf16_f32 v53, v54, v55
	v_cvt_pk_bf16_f32 v54, v48, v49
	v_cvt_pk_bf16_f32 v55, v50, v51
	v_add_u32_e32 v173, 0x40000, v170
	global_store_dwordx4 v173, v[52:55], s[54:55] offset:256
	v_cvt_f32_ubyte0_e32 v128, v194
	v_cvt_f32_ubyte1_e32 v129, v194
	v_cvt_f32_ubyte2_e32 v130, v194
	v_cvt_f32_ubyte3_e32 v131, v194
	v_pk_mul_f32 v[128:129], v[128:129], s[16:17] op_sel_hi:[1,0]
	v_pk_mul_f32 v[130:131], v[130:131], s[16:17] op_sel_hi:[1,0]
	v_pk_fma_f32 v[44:45], v[44:45], v[128:129], v[154:155]
	v_pk_fma_f32 v[46:47], v[46:47], v[130:131], v[154:155]
	v_cvt_f32_ubyte0_e32 v128, v195
	v_cvt_f32_ubyte1_e32 v129, v195
	v_cvt_f32_ubyte2_e32 v130, v195
	v_cvt_f32_ubyte3_e32 v131, v195
	v_pk_mul_f32 v[128:129], v[128:129], s[16:17] op_sel_hi:[1,0]
	v_pk_mul_f32 v[130:131], v[130:131], s[16:17] op_sel_hi:[1,0]
	v_pk_fma_f32 v[40:41], v[40:41], v[128:129], v[154:155]
	v_pk_fma_f32 v[42:43], v[42:43], v[130:131], v[154:155]
	v_cvt_pk_bf16_f32 v44, v44, v45
	v_cvt_pk_bf16_f32 v45, v46, v47
	v_cvt_pk_bf16_f32 v46, v40, v41
	v_cvt_pk_bf16_f32 v47, v42, v43
	v_add_u32_e32 v173, 0x48000, v170
	global_store_dwordx4 v173, v[44:47], s[54:55]
	v_cvt_f32_ubyte0_e32 v128, v196
	v_cvt_f32_ubyte1_e32 v129, v196
	v_cvt_f32_ubyte2_e32 v130, v196
	v_cvt_f32_ubyte3_e32 v131, v196
	v_pk_mul_f32 v[128:129], v[128:129], s[16:17] op_sel_hi:[1,0]
	v_pk_mul_f32 v[130:131], v[130:131], s[16:17] op_sel_hi:[1,0]
	v_pk_fma_f32 v[36:37], v[36:37], v[128:129], v[154:155]
	v_pk_fma_f32 v[38:39], v[38:39], v[130:131], v[154:155]
	v_cvt_f32_ubyte0_e32 v128, v197
	v_cvt_f32_ubyte1_e32 v129, v197
	v_cvt_f32_ubyte2_e32 v130, v197
	v_cvt_f32_ubyte3_e32 v131, v197
	v_pk_mul_f32 v[128:129], v[128:129], s[16:17] op_sel_hi:[1,0]
	v_pk_mul_f32 v[130:131], v[130:131], s[16:17] op_sel_hi:[1,0]
	v_pk_fma_f32 v[32:33], v[32:33], v[128:129], v[154:155]
	v_pk_fma_f32 v[34:35], v[34:35], v[130:131], v[154:155]
	v_cvt_pk_bf16_f32 v36, v36, v37
	v_cvt_pk_bf16_f32 v37, v38, v39
	v_cvt_pk_bf16_f32 v38, v32, v33
	v_cvt_pk_bf16_f32 v39, v34, v35
	v_add_u32_e32 v173, 0x48000, v170
	global_store_dwordx4 v173, v[36:39], s[54:55] offset:256
	v_cvt_f32_ubyte0_e32 v128, v198
	v_cvt_f32_ubyte1_e32 v129, v198
	v_cvt_f32_ubyte2_e32 v130, v198
	v_cvt_f32_ubyte3_e32 v131, v198
	v_pk_mul_f32 v[128:129], v[128:129], s[16:17] op_sel_hi:[1,0]
	v_pk_mul_f32 v[130:131], v[130:131], s[16:17] op_sel_hi:[1,0]
	v_pk_fma_f32 v[28:29], v[28:29], v[128:129], v[154:155]
	v_pk_fma_f32 v[30:31], v[30:31], v[130:131], v[154:155]
	v_cvt_f32_ubyte0_e32 v128, v199
	v_cvt_f32_ubyte1_e32 v129, v199
	v_cvt_f32_ubyte2_e32 v130, v199
	v_cvt_f32_ubyte3_e32 v131, v199
	v_pk_mul_f32 v[128:129], v[128:129], s[16:17] op_sel_hi:[1,0]
	v_pk_mul_f32 v[130:131], v[130:131], s[16:17] op_sel_hi:[1,0]
	v_pk_fma_f32 v[24:25], v[24:25], v[128:129], v[154:155]
	v_pk_fma_f32 v[26:27], v[26:27], v[130:131], v[154:155]
	v_cvt_pk_bf16_f32 v28, v28, v29
	v_cvt_pk_bf16_f32 v29, v30, v31
	v_cvt_pk_bf16_f32 v30, v24, v25
	v_cvt_pk_bf16_f32 v31, v26, v27
	v_add_u32_e32 v173, 0x50000, v170
	global_store_dwordx4 v173, v[28:31], s[54:55]
	v_cvt_f32_ubyte0_e32 v128, v200
	v_cvt_f32_ubyte1_e32 v129, v200
	v_cvt_f32_ubyte2_e32 v130, v200
	v_cvt_f32_ubyte3_e32 v131, v200
	v_pk_mul_f32 v[128:129], v[128:129], s[16:17] op_sel_hi:[1,0]
	v_pk_mul_f32 v[130:131], v[130:131], s[16:17] op_sel_hi:[1,0]
	v_pk_fma_f32 v[20:21], v[20:21], v[128:129], v[154:155]
	v_pk_fma_f32 v[22:23], v[22:23], v[130:131], v[154:155]
	v_cvt_f32_ubyte0_e32 v128, v201
	v_cvt_f32_ubyte1_e32 v129, v201
	v_cvt_f32_ubyte2_e32 v130, v201
	v_cvt_f32_ubyte3_e32 v131, v201
	v_pk_mul_f32 v[128:129], v[128:129], s[16:17] op_sel_hi:[1,0]
	v_pk_mul_f32 v[130:131], v[130:131], s[16:17] op_sel_hi:[1,0]
	v_pk_fma_f32 v[16:17], v[16:17], v[128:129], v[154:155]
	v_pk_fma_f32 v[18:19], v[18:19], v[130:131], v[154:155]
	v_cvt_pk_bf16_f32 v20, v20, v21
	v_cvt_pk_bf16_f32 v21, v22, v23
	v_cvt_pk_bf16_f32 v22, v16, v17
	v_cvt_pk_bf16_f32 v23, v18, v19
	v_add_u32_e32 v173, 0x50000, v170
	global_store_dwordx4 v173, v[20:23], s[54:55] offset:256
	v_cvt_f32_ubyte0_e32 v128, v202
	v_cvt_f32_ubyte1_e32 v129, v202
	v_cvt_f32_ubyte2_e32 v130, v202
	v_cvt_f32_ubyte3_e32 v131, v202
	v_pk_mul_f32 v[128:129], v[128:129], s[16:17] op_sel_hi:[1,0]
	v_pk_mul_f32 v[130:131], v[130:131], s[16:17] op_sel_hi:[1,0]
	v_pk_fma_f32 v[12:13], v[12:13], v[128:129], v[154:155]
	v_pk_fma_f32 v[14:15], v[14:15], v[130:131], v[154:155]
	v_cvt_f32_ubyte0_e32 v128, v203
	v_cvt_f32_ubyte1_e32 v129, v203
	v_cvt_f32_ubyte2_e32 v130, v203
	v_cvt_f32_ubyte3_e32 v131, v203
	v_pk_mul_f32 v[128:129], v[128:129], s[16:17] op_sel_hi:[1,0]
	v_pk_mul_f32 v[130:131], v[130:131], s[16:17] op_sel_hi:[1,0]
	v_pk_fma_f32 v[8:9], v[8:9], v[128:129], v[154:155]
	v_pk_fma_f32 v[10:11], v[10:11], v[130:131], v[154:155]
	v_cvt_pk_bf16_f32 v12, v12, v13
	v_cvt_pk_bf16_f32 v13, v14, v15
	v_cvt_pk_bf16_f32 v14, v8, v9
	v_cvt_pk_bf16_f32 v15, v10, v11
	v_add_u32_e32 v173, 0x58000, v170
	global_store_dwordx4 v173, v[12:15], s[54:55]
	v_cvt_f32_ubyte0_e32 v128, v204
	v_cvt_f32_ubyte1_e32 v129, v204
	v_cvt_f32_ubyte2_e32 v130, v204
	v_cvt_f32_ubyte3_e32 v131, v204
	v_pk_mul_f32 v[128:129], v[128:129], s[16:17] op_sel_hi:[1,0]
	v_pk_mul_f32 v[130:131], v[130:131], s[16:17] op_sel_hi:[1,0]
	v_pk_fma_f32 v[4:5], v[4:5], v[128:129], v[154:155]
	v_pk_fma_f32 v[6:7], v[6:7], v[130:131], v[154:155]
	v_cvt_f32_ubyte0_e32 v128, v205
	v_cvt_f32_ubyte1_e32 v129, v205
	v_cvt_f32_ubyte2_e32 v130, v205
	v_cvt_f32_ubyte3_e32 v131, v205
	v_pk_mul_f32 v[128:129], v[128:129], s[16:17] op_sel_hi:[1,0]
	v_pk_mul_f32 v[130:131], v[130:131], s[16:17] op_sel_hi:[1,0]
	v_pk_fma_f32 v[0:1], v[0:1], v[128:129], v[154:155]
	v_pk_fma_f32 v[2:3], v[2:3], v[130:131], v[154:155]
	v_cvt_pk_bf16_f32 v4, v4, v5
	v_cvt_pk_bf16_f32 v5, v6, v7
	v_cvt_pk_bf16_f32 v6, v0, v1
	v_cvt_pk_bf16_f32 v7, v2, v3
	v_add_u32_e32 v173, 0x58000, v170
	global_store_dwordx4 v173, v[4:7], s[54:55] offset:256
.Lbrb_end:
	s_and_b64 vcc, exec, s[2:3]
	s_mov_b64 s[2:3], -1
	s_cbranch_vccnz .LBB0_2021
	s_andn2_b64 vcc, exec, s[6:7]
	s_cbranch_vccnz .LBB0_2020
	s_barrier
	s_branch .LBB0_2020
